# non-temporal hint on the streaming bf16 output stores of the input-projection and ffn-in epilogues
# speedup vs baseline: 1.0246x; 1.0106x over previous
; #define LAS __attribute__((address_space(3)))
; __device__ __forceinline__ unsigned cvt_pk_bf16(float lo, float hi) { unsigned r; asm volatile("v_cvt_pk_bf16_f32 %0, %1, %2" : "=v"(r) : "v"(lo), "v"(hi)); return r; }
; __device__ __forceinline__ float sigmoidf_(float v) { return __builtin_amdgcn_rcpf(1.f + __expf(-v)); }
;     __device__ __forceinline__ void operator()(const f32x4 (&acc)[2][2][4][2], const pg8::Unit& u, int wr, int wc, int fr, int fq, LAS unsigned char* sp) const {
;     ...
;         const int cw0 = wc * 32 + 8 * fq;
; #pragma unroll
;         for (int ai = 0; ai < 2; ++ai)
; #pragma unroll
;             for (int m = 0; m < 4; ++m) {
;                 const int row = row0 + ai * 128 + m * 16; const float s = rsl[ai * 128 + m * 16];
; #pragma unroll
;                 for (int bj = 0; bj < 2; ++bj) {
;                     f32x4 v0 = acc[ai][bj][m][0] * s, v1 = acc[ai][bj][m][1] * s;
;                     const int col = colt + bj * 128 + cw0;
;                     if (act == 2) { const f32x4 b0 = *(const LAS f32x4*)(bsl + bj * 128 + cw0), b1 = *(const LAS f32x4*)(bsl + bj * 128 + cw0 + 4);
;                         v0 += b0; v1 += b1;
; #pragma unroll
;                         for (int j = 0; j < 4; ++j) { v0[j] = sigmoidf_(v0[j]); v1[j] = sigmoidf_(v1[j]); } }
;                     else if (act == 1) {
; #pragma unroll
;                         for (int j = 0; j < 4; ++j) { v0[j] = v0[j] * sigmoidf_(v0[j]); v1[j] = v1[j] * sigmoidf_(v1[j]); } }
;                     u32x4 w; w.x = cvt_pk_bf16(v0[0], v0[1]); w.y = cvt_pk_bf16(v0[2], v0[3]); w.z = cvt_pk_bf16(v1[0], v1[1]); w.w = cvt_pk_bf16(v1[2], v1[3]);
;                     *(u32x4*)(dst + (size_t)row * pitch + col) = w;
;                 }
.LBB0_33:
	s_lshl_b32 s19, s69, 11
	s_and_b32 s19, s19, 0x800
	v_add_u32_e32 v161, s19, v157
	s_lshl_b32 s19, s68, 8
	s_add_i32 s23, s19, 0xfffff500
	ds_read_b32 v162, v161
	s_cmp_lt_i32 s68, 11
	s_cselect_b32 s19, s19, s23
	s_cselect_b32 s23, 0, 0xb000000
	s_add_u32 s26, s61, s23
	s_addc_u32 s27, s62, 0
	v_lshl_add_u32 v163, s52, 8, v145
	v_or_b32_e32 v164, s19, v159
	v_mov_b64_e32 v[142:143], s[26:27]
	s_waitcnt lgkmcnt(0)
	v_pk_mul_f32 v[126:127], v[126:127], v[162:163] op_sel_hi:[1,0]
	v_pk_mul_f32 v[122:123], v[122:123], v[162:163] op_sel_hi:[1,0]
	v_ashrrev_i32_e32 v165, 31, v164
	v_mad_i64_i32 v[166:167], s[26:27], v163, s31, v[142:143]
	v_pk_mul_f32 v[128:129], v[128:129], v[162:163] op_sel_hi:[1,0]
	v_pk_mul_f32 v[168:169], v[124:125], v[162:163] op_sel_hi:[1,0]
	v_cvt_pk_bf16_f32 v124, v126, v127
	v_cvt_pk_bf16_f32 v125, v128, v129
	v_cvt_pk_bf16_f32 v126, v122, v123
	v_lshlrev_b64 v[122:123], 1, v[164:165]
	v_lshl_add_u64 v[128:129], v[166:167], 0, v[122:123]
	v_cvt_pk_bf16_f32 v127, v168, v169
	global_store_dwordx4 v[128:129], v[124:127], off nt
	v_pk_mul_f32 v[118:119], v[118:119], v[162:163] op_sel_hi:[1,0]
	v_pk_mul_f32 v[120:121], v[120:121], v[162:163] op_sel_hi:[1,0]
	v_pk_mul_f32 v[124:125], v[112:113], v[162:163] op_sel_hi:[1,0]
	v_pk_mul_f32 v[112:113], v[110:111], v[162:163] op_sel_hi:[1,0]
	v_cvt_pk_bf16_f32 v110, v118, v119
	v_cvt_pk_bf16_f32 v111, v120, v121
	s_andn2_b64 vcc, exec, s[6:7]
	v_cvt_pk_bf16_f32 v112, v112, v113
	v_cvt_pk_bf16_f32 v113, v124, v125
	ds_read_b32 v118, v161 offset:64
	global_store_dwordx4 v[128:129], v[110:113], off offset:256 nt
	s_mov_b64 s[6:7], -1
	s_waitcnt lgkmcnt(0)
	v_pk_mul_f32 v[114:115], v[114:115], v[118:119] op_sel_hi:[1,0]
	v_or_b32_e32 v110, 16, v163
	v_mad_i64_i32 v[110:111], s[26:27], v110, s31, v[142:143]
	v_pk_mul_f32 v[112:113], v[116:117], v[118:119] op_sel_hi:[1,0]
	v_pk_mul_f32 v[116:117], v[108:109], v[118:119] op_sel_hi:[1,0]
	v_pk_mul_f32 v[108:109], v[106:107], v[118:119] op_sel_hi:[1,0]
	v_cvt_pk_bf16_f32 v106, v114, v115
	v_cvt_pk_bf16_f32 v107, v112, v113
	v_lshl_add_u64 v[110:111], v[110:111], 0, v[122:123]
	v_cvt_pk_bf16_f32 v108, v108, v109
	v_cvt_pk_bf16_f32 v109, v116, v117
	global_store_dwordx4 v[110:111], v[106:109], off nt
	v_pk_mul_f32 v[102:103], v[102:103], v[118:119] op_sel_hi:[1,0]
	v_pk_mul_f32 v[104:105], v[104:105], v[118:119] op_sel_hi:[1,0]
	v_pk_mul_f32 v[106:107], v[96:97], v[118:119] op_sel_hi:[1,0]
	v_pk_mul_f32 v[96:97], v[94:95], v[118:119] op_sel_hi:[1,0]
	v_cvt_pk_bf16_f32 v94, v102, v103
	v_cvt_pk_bf16_f32 v95, v104, v105
	s_nop 0
	v_cvt_pk_bf16_f32 v96, v96, v97
	v_cvt_pk_bf16_f32 v97, v106, v107
	ds_read_b32 v102, v161 offset:128
	global_store_dwordx4 v[110:111], v[94:97], off offset:256 nt
	s_waitcnt lgkmcnt(0)
	v_pk_mul_f32 v[98:99], v[98:99], v[102:103] op_sel_hi:[1,0]
	v_or_b32_e32 v94, 32, v163
	v_mad_i64_i32 v[94:95], s[26:27], v94, s31, v[142:143]
	v_pk_mul_f32 v[96:97], v[100:101], v[102:103] op_sel_hi:[1,0]
	v_pk_mul_f32 v[100:101], v[92:93], v[102:103] op_sel_hi:[1,0]
	v_pk_mul_f32 v[92:93], v[90:91], v[102:103] op_sel_hi:[1,0]
	v_cvt_pk_bf16_f32 v90, v98, v99
	v_cvt_pk_bf16_f32 v91, v96, v97
	v_lshl_add_u64 v[94:95], v[94:95], 0, v[122:123]
	v_cvt_pk_bf16_f32 v92, v92, v93
	v_cvt_pk_bf16_f32 v93, v100, v101
	global_store_dwordx4 v[94:95], v[90:93], off nt
	v_pk_mul_f32 v[86:87], v[86:87], v[102:103] op_sel_hi:[1,0]
	v_pk_mul_f32 v[88:89], v[88:89], v[102:103] op_sel_hi:[1,0]
	v_pk_mul_f32 v[90:91], v[80:81], v[102:103] op_sel_hi:[1,0]
	v_pk_mul_f32 v[80:81], v[78:79], v[102:103] op_sel_hi:[1,0]
	v_cvt_pk_bf16_f32 v78, v86, v87
	v_cvt_pk_bf16_f32 v79, v88, v89
	s_nop 0
	v_cvt_pk_bf16_f32 v80, v80, v81
	v_cvt_pk_bf16_f32 v81, v90, v91
	ds_read_b32 v86, v161 offset:192
	global_store_dwordx4 v[94:95], v[78:81], off offset:256 nt
	s_waitcnt lgkmcnt(0)
	v_pk_mul_f32 v[82:83], v[82:83], v[86:87] op_sel_hi:[1,0]
	v_or_b32_e32 v78, 48, v163
	v_mad_i64_i32 v[78:79], s[26:27], v78, s31, v[142:143]
	v_pk_mul_f32 v[80:81], v[84:85], v[86:87] op_sel_hi:[1,0]
	v_pk_mul_f32 v[84:85], v[76:77], v[86:87] op_sel_hi:[1,0]
	v_pk_mul_f32 v[76:77], v[74:75], v[86:87] op_sel_hi:[1,0]
	v_cvt_pk_bf16_f32 v74, v82, v83
	v_cvt_pk_bf16_f32 v75, v80, v81
	v_lshl_add_u64 v[78:79], v[78:79], 0, v[122:123]
	v_cvt_pk_bf16_f32 v76, v76, v77
	v_cvt_pk_bf16_f32 v77, v84, v85
	global_store_dwordx4 v[78:79], v[74:77], off nt
	v_pk_mul_f32 v[70:71], v[70:71], v[86:87] op_sel_hi:[1,0]
	v_pk_mul_f32 v[72:73], v[72:73], v[86:87] op_sel_hi:[1,0]
	v_pk_mul_f32 v[74:75], v[68:69], v[86:87] op_sel_hi:[1,0]
	v_pk_mul_f32 v[68:69], v[66:67], v[86:87] op_sel_hi:[1,0]
	v_cvt_pk_bf16_f32 v66, v70, v71
	v_cvt_pk_bf16_f32 v67, v72, v73
	s_nop 0
	v_cvt_pk_bf16_f32 v68, v68, v69
	v_cvt_pk_bf16_f32 v69, v74, v75
	ds_read_b32 v70, v161 offset:512
	global_store_dwordx4 v[78:79], v[66:69], off offset:256 nt
	s_waitcnt lgkmcnt(0)
; #define LAS __attribute__((address_space(3)))
; __device__ __forceinline__ unsigned cvt_pk_bf16(float lo, float hi) { unsigned r; asm volatile("v_cvt_pk_bf16_f32 %0, %1, %2" : "=v"(r) : "v"(lo), "v"(hi)); return r; }
; __device__ __forceinline__ float sigmoidf_(float v) { return __builtin_amdgcn_rcpf(1.f + __expf(-v)); }
; __device__ __forceinline__ float row_scale(const float* ssq, int row) {
;     const f32x4* p = (const f32x4*)(ssq + (size_t)row * 16); const f32x4 a = p[0], b = p[1], c = p[2], d = p[3];
;     const float s = ((a.x + a.y) + (a.z + a.w)) + ((b.x + b.y) + (b.z + b.w)) + ((c.x + c.y) + (c.z + c.w)) + ((d.x + d.y) + (d.z + d.w));
;     return rsqrtf(s * (1.f / DM) + EPS);
; }
;     __device__ __forceinline__ void operator()(const f32x4 (&acc)[2][2][4][2], const pg8::Unit& u, int wr, int wc, int fr, int fq, LAS unsigned char* sp) const {
;     ...
;             for (int m = 0; m < 4; ++m) {
;                 const int row = row0 + ai * 128 + m * 16; const float s = rsl[ai * 128 + m * 16];
; #pragma unroll
;                 for (int bj = 0; bj < 2; ++bj) {
;                     f32x4 v0 = acc[ai][bj][m][0] * s, v1 = acc[ai][bj][m][1] * s;
;                     const int col = colt + bj * 128 + cw0;
;                     if (act == 2) { const f32x4 b0 = *(const LAS f32x4*)(bsl + bj * 128 + cw0), b1 = *(const LAS f32x4*)(bsl + bj * 128 + cw0 + 4);
;                         v0 += b0; v1 += b1;
; #pragma unroll
;                         for (int j = 0; j < 4; ++j) { v0[j] = sigmoidf_(v0[j]); v1[j] = sigmoidf_(v1[j]); } }
;                     else if (act == 1) {
; #pragma unroll
;                         for (int j = 0; j < 4; ++j) { v0[j] = v0[j] * sigmoidf_(v0[j]); v1[j] = v1[j] * sigmoidf_(v1[j]); } }
;                     u32x4 w; w.x = cvt_pk_bf16(v0[0], v0[1]); w.y = cvt_pk_bf16(v0[2], v0[3]); w.z = cvt_pk_bf16(v1[0], v1[1]); w.w = cvt_pk_bf16(v1[2], v1[3]);
;                     *(u32x4*)(dst + (size_t)row * pitch + col) = w;
;                 }
	v_pk_mul_f32 v[62:63], v[62:63], v[70:71] op_sel_hi:[1,0]
	v_add_u32_e32 v66, 0x80, v163
	v_mad_i64_i32 v[66:67], s[26:27], v66, s31, v[142:143]
	v_pk_mul_f32 v[64:65], v[64:65], v[70:71] op_sel_hi:[1,0]
	v_pk_mul_f32 v[68:69], v[60:61], v[70:71] op_sel_hi:[1,0]
	v_pk_mul_f32 v[60:61], v[58:59], v[70:71] op_sel_hi:[1,0]
	v_cvt_pk_bf16_f32 v58, v62, v63
	v_cvt_pk_bf16_f32 v59, v64, v65
	v_lshl_add_u64 v[62:63], v[66:67], 0, v[122:123]
	v_cvt_pk_bf16_f32 v60, v60, v61
	v_cvt_pk_bf16_f32 v61, v68, v69
	global_store_dwordx4 v[62:63], v[58:61], off nt
	v_pk_mul_f32 v[54:55], v[54:55], v[70:71] op_sel_hi:[1,0]
	v_pk_mul_f32 v[56:57], v[56:57], v[70:71] op_sel_hi:[1,0]
	v_pk_mul_f32 v[58:59], v[48:49], v[70:71] op_sel_hi:[1,0]
	v_pk_mul_f32 v[48:49], v[46:47], v[70:71] op_sel_hi:[1,0]
	v_cvt_pk_bf16_f32 v46, v54, v55
	v_cvt_pk_bf16_f32 v47, v56, v57
	s_nop 0
	v_cvt_pk_bf16_f32 v48, v48, v49
	v_cvt_pk_bf16_f32 v49, v58, v59
	ds_read_b32 v54, v161 offset:576
	global_store_dwordx4 v[62:63], v[46:49], off offset:256 nt
	s_waitcnt lgkmcnt(0)
	v_pk_mul_f32 v[50:51], v[50:51], v[54:55] op_sel_hi:[1,0]
	v_add_u32_e32 v46, 0x90, v163
	v_mad_i64_i32 v[46:47], s[26:27], v46, s31, v[142:143]
	v_pk_mul_f32 v[48:49], v[52:53], v[54:55] op_sel_hi:[1,0]
	v_pk_mul_f32 v[52:53], v[44:45], v[54:55] op_sel_hi:[1,0]
	v_pk_mul_f32 v[44:45], v[42:43], v[54:55] op_sel_hi:[1,0]
	v_cvt_pk_bf16_f32 v42, v50, v51
	v_cvt_pk_bf16_f32 v43, v48, v49
	v_lshl_add_u64 v[46:47], v[46:47], 0, v[122:123]
	v_cvt_pk_bf16_f32 v44, v44, v45
	v_cvt_pk_bf16_f32 v45, v52, v53
	global_store_dwordx4 v[46:47], v[42:45], off nt
	v_pk_mul_f32 v[38:39], v[38:39], v[54:55] op_sel_hi:[1,0]
	v_pk_mul_f32 v[40:41], v[40:41], v[54:55] op_sel_hi:[1,0]
	v_pk_mul_f32 v[42:43], v[32:33], v[54:55] op_sel_hi:[1,0]
	v_pk_mul_f32 v[32:33], v[30:31], v[54:55] op_sel_hi:[1,0]
	v_cvt_pk_bf16_f32 v30, v38, v39
	v_cvt_pk_bf16_f32 v31, v40, v41
	s_nop 0
	v_cvt_pk_bf16_f32 v32, v32, v33
	v_cvt_pk_bf16_f32 v33, v42, v43
	ds_read_b32 v38, v161 offset:640
	global_store_dwordx4 v[46:47], v[30:33], off offset:256 nt
	s_waitcnt lgkmcnt(0)
	v_pk_mul_f32 v[34:35], v[34:35], v[38:39] op_sel_hi:[1,0]
	v_add_u32_e32 v30, 0xa0, v163
	v_mad_i64_i32 v[30:31], s[26:27], v30, s31, v[142:143]
	v_pk_mul_f32 v[32:33], v[36:37], v[38:39] op_sel_hi:[1,0]
	v_pk_mul_f32 v[36:37], v[28:29], v[38:39] op_sel_hi:[1,0]
	v_pk_mul_f32 v[28:29], v[26:27], v[38:39] op_sel_hi:[1,0]
	v_cvt_pk_bf16_f32 v26, v34, v35
	v_cvt_pk_bf16_f32 v27, v32, v33
	v_lshl_add_u64 v[30:31], v[30:31], 0, v[122:123]
	v_cvt_pk_bf16_f32 v28, v28, v29
	v_cvt_pk_bf16_f32 v29, v36, v37
	global_store_dwordx4 v[30:31], v[26:29], off nt
	v_pk_mul_f32 v[22:23], v[22:23], v[38:39] op_sel_hi:[1,0]
	v_pk_mul_f32 v[24:25], v[24:25], v[38:39] op_sel_hi:[1,0]
	v_pk_mul_f32 v[26:27], v[16:17], v[38:39] op_sel_hi:[1,0]
	v_pk_mul_f32 v[16:17], v[14:15], v[38:39] op_sel_hi:[1,0]
	v_cvt_pk_bf16_f32 v14, v22, v23
	v_cvt_pk_bf16_f32 v15, v24, v25
	s_nop 0
	v_cvt_pk_bf16_f32 v16, v16, v17
	v_cvt_pk_bf16_f32 v17, v26, v27
	ds_read_b32 v22, v161 offset:704
	global_store_dwordx4 v[30:31], v[14:17], off offset:256 nt
	s_waitcnt lgkmcnt(0)
	v_pk_mul_f32 v[18:19], v[18:19], v[22:23] op_sel_hi:[1,0]
	v_add_u32_e32 v14, 0xb0, v163
	v_mad_i64_i32 v[14:15], s[26:27], v14, s31, v[142:143]
	v_pk_mul_f32 v[16:17], v[20:21], v[22:23] op_sel_hi:[1,0]
	v_pk_mul_f32 v[20:21], v[12:13], v[22:23] op_sel_hi:[1,0]
	v_pk_mul_f32 v[12:13], v[10:11], v[22:23] op_sel_hi:[1,0]
	v_cvt_pk_bf16_f32 v10, v18, v19
	v_cvt_pk_bf16_f32 v11, v16, v17
	v_lshl_add_u64 v[14:15], v[14:15], 0, v[122:123]
	v_cvt_pk_bf16_f32 v12, v12, v13
	v_cvt_pk_bf16_f32 v13, v20, v21
	global_store_dwordx4 v[14:15], v[10:13], off nt
	v_pk_mul_f32 v[8:9], v[8:9], v[22:23] op_sel_hi:[1,0]
	v_pk_mul_f32 v[6:7], v[6:7], v[22:23] op_sel_hi:[1,0]
	v_pk_mul_f32 v[10:11], v[4:5], v[22:23] op_sel_hi:[1,0]
	v_pk_mul_f32 v[4:5], v[2:3], v[22:23] op_sel_hi:[1,0]
	v_cvt_pk_bf16_f32 v2, v6, v7
	v_cvt_pk_bf16_f32 v3, v8, v9
	s_nop 0
	v_cvt_pk_bf16_f32 v4, v4, v5
	v_cvt_pk_bf16_f32 v5, v10, v11
	global_store_dwordx4 v[14:15], v[2:5], off offset:256 nt
	s_cbranch_vccnz .LBB0_26
	s_and_saveexec_b64 s[6:7], s[4:5]
	s_cbranch_execz .LBB0_36
	v_lshl_add_u32 v2, s22, 8, v144
	v_ashrrev_i32_e32 v3, 31, v2
	v_lshlrev_b64 v[2:3], 6, v[2:3]
	v_lshl_add_u64 v[14:15], v[130:131], 0, v[2:3]
	global_load_dwordx4 v[2:5], v[14:15], off offset:48
	global_load_dwordx4 v[6:9], v[14:15], off offset:32
	global_load_dwordx4 v[10:13], v[14:15], off offset:16
	s_nop 0
	global_load_dwordx4 v[14:17], v[14:15], off
	s_lshl_b32 s19, s67, 11
	s_and_b32 s19, s19, 0x800
	s_waitcnt vmcnt(0)
	v_add_f32_e32 v6, v6, v7
	v_add_f32_e32 v8, v8, v9
	v_mov_b32_e32 v18, v15
	v_mov_b32_e32 v19, v16
	v_mov_b32_e32 v15, v17
	v_mov_b32_e32 v16, v11
	v_mov_b32_e32 v17, v12
	v_mov_b32_e32 v11, v13
	v_pk_add_f32 v[14:15], v[18:19], v[14:15]
	v_pk_add_f32 v[10:11], v[16:17], v[10:11]
	v_pk_add_f32 v[14:15], v[14:15], v[14:15] op_sel:[0,1] op_sel_hi:[1,0]
	v_pk_add_f32 v[10:11], v[10:11], v[10:11] op_sel:[0,1] op_sel_hi:[1,0]
	v_mov_b32_e32 v15, v2
	v_mov_b32_e32 v11, v3
	v_mov_b32_e32 v7, v4
	v_mov_b32_e32 v9, v5
	v_pk_add_f32 v[2:3], v[14:15], v[10:11]
	v_pk_add_f32 v[4:5], v[6:7], v[8:9]
	s_nop 0
	v_pk_add_f32 v[2:3], v[2:3], v[4:5]
	s_nop 0
	v_add_f32_e32 v2, v2, v3
	v_fmamk_f32 v2, v2, 0x3a800000, v184
	v_cmp_gt_f32_e32 vcc, s74, v2
	v_mul_f32_e32 v3, 0x4b800000, v2
	s_nop 0
	v_cndmask_b32_e32 v2, v2, v3, vcc
	v_rsq_f32_e32 v2, v2
	s_nop 0
	v_mul_f32_e32 v3, 0x45800000, v2
	v_cndmask_b32_e32 v2, v2, v3, vcc
	v_add_u32_e32 v3, s19, v158
	ds_write_b32 v3, v2

; __device__ __forceinline__ void reduce_hx(unsigned char* ws, const int tid, const int bx, const int G) {
;     const f32x4* part = (const f32x4*)(ws + WS_PART); f32x4* hx = (f32x4*)(ws + WS_HX);
;     for (int e = bx * NTHR + tid; e < 64 * 1024 / 4; e += G * NTHR) { f32x4 s = (f32x4){0.f, 0.f, 0.f, 0.f};
; #pragma unroll 16
;         for (int kc = 0; kc < 32; ++kc) s += part[(size_t)kc * 16384 + e];
;         hx[e] = s; }
; }
.LBB0_221:
	v_lshl_add_u64 v[70:71], v[8:9], 0, s[48:49]
	v_add_co_u32_e32 v10, vcc, 0x1f600000, v70
	s_add_u32 s48, s48, 0x400000
	s_nop 0
	v_addc_co_u32_e32 v11, vcc, 0, v71, vcc
	v_add_co_u32_e32 v14, vcc, 0x1f640000, v70
	s_addc_u32 s49, s49, 0
	s_nop 0
	v_addc_co_u32_e32 v15, vcc, 0, v71, vcc
	v_add_co_u32_e32 v18, vcc, 0x1f680000, v70
	global_load_dwordx4 v[10:13], v[10:11], off
	s_nop 0
	global_load_dwordx4 v[14:17], v[14:15], off
	v_addc_co_u32_e32 v19, vcc, 0, v71, vcc
	v_add_co_u32_e32 v22, vcc, 0x1f6c0000, v70
	s_cmp_eq_u32 s48, 0x800000
	s_nop 0
	v_addc_co_u32_e32 v23, vcc, 0, v71, vcc
	v_add_co_u32_e32 v26, vcc, 0x1f700000, v70
	global_load_dwordx4 v[18:21], v[18:19], off
	s_nop 0
	global_load_dwordx4 v[22:25], v[22:23], off
	v_addc_co_u32_e32 v27, vcc, 0, v71, vcc
	v_add_co_u32_e32 v30, vcc, 0x1f740000, v70
	s_waitcnt vmcnt(0)
	v_pk_add_f32 v[4:5], v[4:5], v[12:13]
	v_addc_co_u32_e32 v31, vcc, 0, v71, vcc
	v_add_co_u32_e32 v34, vcc, 0x1f780000, v70
	global_load_dwordx4 v[26:29], v[26:27], off
	s_nop 0
	global_load_dwordx4 v[30:33], v[30:31], off
	v_addc_co_u32_e32 v35, vcc, 0, v71, vcc
	v_add_co_u32_e32 v38, vcc, 0x1f7c0000, v70
	v_pk_add_f32 v[2:3], v[2:3], v[10:11]
	s_nop 0
	v_addc_co_u32_e32 v39, vcc, 0, v71, vcc
	v_add_co_u32_e32 v42, vcc, 0x1f800000, v70
	global_load_dwordx4 v[34:37], v[34:35], off
	s_nop 0
	global_load_dwordx4 v[38:41], v[38:39], off
	v_addc_co_u32_e32 v43, vcc, 0, v71, vcc
	v_add_co_u32_e32 v46, vcc, 0x1f840000, v70
	v_pk_add_f32 v[4:5], v[4:5], v[16:17]
	s_nop 0
	v_addc_co_u32_e32 v47, vcc, 0, v71, vcc
	v_add_co_u32_e32 v50, vcc, 0x1f880000, v70
	global_load_dwordx4 v[42:45], v[42:43], off
	s_nop 0
	global_load_dwordx4 v[46:49], v[46:47], off
	v_addc_co_u32_e32 v51, vcc, 0, v71, vcc
	v_add_co_u32_e32 v54, vcc, 0x1f8c0000, v70
	v_pk_add_f32 v[2:3], v[2:3], v[14:15]
	s_nop 0
	v_addc_co_u32_e32 v55, vcc, 0, v71, vcc
	v_add_co_u32_e32 v58, vcc, 0x1f900000, v70
	global_load_dwordx4 v[50:53], v[50:51], off
	s_nop 0
	global_load_dwordx4 v[54:57], v[54:55], off
	v_addc_co_u32_e32 v59, vcc, 0, v71, vcc
	v_add_co_u32_e32 v62, vcc, 0x1f940000, v70
	v_pk_add_f32 v[4:5], v[4:5], v[20:21]
	s_nop 0
	v_addc_co_u32_e32 v63, vcc, 0, v71, vcc
	v_add_co_u32_e32 v66, vcc, 0x1f980000, v70
	global_load_dwordx4 v[58:61], v[58:59], off
	s_nop 0
	global_load_dwordx4 v[62:65], v[62:63], off
	v_addc_co_u32_e32 v67, vcc, 0, v71, vcc
	v_add_co_u32_e32 v70, vcc, 0x1f9c0000, v70
	global_load_dwordx4 v[66:69], v[66:67], off
	s_nop 0
	v_addc_co_u32_e32 v71, vcc, 0, v71, vcc
	global_load_dwordx4 v[70:73], v[70:71], off
	v_pk_add_f32 v[2:3], v[2:3], v[18:19]
	v_pk_add_f32 v[4:5], v[4:5], v[24:25]
	v_pk_add_f32 v[2:3], v[2:3], v[22:23]
	s_waitcnt vmcnt(11)
	v_pk_add_f32 v[4:5], v[4:5], v[28:29]
	v_pk_add_f32 v[2:3], v[2:3], v[26:27]
	s_waitcnt vmcnt(10)
	v_pk_add_f32 v[4:5], v[4:5], v[32:33]
	v_pk_add_f32 v[2:3], v[2:3], v[30:31]
	s_waitcnt vmcnt(9)
	v_pk_add_f32 v[4:5], v[4:5], v[36:37]
	v_pk_add_f32 v[2:3], v[2:3], v[34:35]
	s_waitcnt vmcnt(8)
	v_pk_add_f32 v[4:5], v[4:5], v[40:41]
	v_pk_add_f32 v[2:3], v[2:3], v[38:39]
	s_waitcnt vmcnt(7)
	v_pk_add_f32 v[4:5], v[4:5], v[44:45]
	v_pk_add_f32 v[2:3], v[2:3], v[42:43]
	s_waitcnt vmcnt(6)
	v_pk_add_f32 v[4:5], v[4:5], v[48:49]
	v_pk_add_f32 v[2:3], v[2:3], v[46:47]
	s_waitcnt vmcnt(5)
	v_pk_add_f32 v[4:5], v[4:5], v[52:53]
	v_pk_add_f32 v[2:3], v[2:3], v[50:51]
	s_waitcnt vmcnt(4)
	v_pk_add_f32 v[4:5], v[4:5], v[56:57]
	v_pk_add_f32 v[2:3], v[2:3], v[54:55]
	s_waitcnt vmcnt(3)
	v_pk_add_f32 v[4:5], v[4:5], v[60:61]
	v_pk_add_f32 v[2:3], v[2:3], v[58:59]
	s_waitcnt vmcnt(2)
	v_pk_add_f32 v[4:5], v[4:5], v[64:65]
	v_pk_add_f32 v[2:3], v[2:3], v[62:63]
	s_waitcnt vmcnt(1)
	v_pk_add_f32 v[4:5], v[4:5], v[68:69]
	v_pk_add_f32 v[2:3], v[2:3], v[66:67]
	s_waitcnt vmcnt(0)
	v_pk_add_f32 v[4:5], v[4:5], v[72:73]
	v_pk_add_f32 v[2:3], v[2:3], v[70:71]
	s_cbranch_scc0 .LBB0_221
	v_ashrrev_i32_e32 v7, 31, v6
	v_lshl_add_u64 v[10:11], v[6:7], 4, s[12:13]
	v_add_u32_e32 v6, s14, v6
	s_movk_i32 s11, 0x3fff
	v_cmp_lt_i32_e32 vcc, s11, v6
	s_or_b64 s[22:23], vcc, s[22:23]
	v_lshl_add_u64 v[8:9], v[8:9], 0, s[18:19]
	global_store_dwordx4 v[10:11], v[2:5], off nt
	s_andn2_b64 exec, exec, s[22:23]
	s_cbranch_execnz .LBB0_220

; #define LAS __attribute__((address_space(3)))
; __device__ __forceinline__ unsigned cvt_pk_bf16(float lo, float hi) { unsigned r; asm volatile("v_cvt_pk_bf16_f32 %0, %1, %2" : "=v"(r) : "v"(lo), "v"(hi)); return r; }
; __device__ __forceinline__ float sigmoidf_(float v) { return __builtin_amdgcn_rcpf(1.f + __expf(-v)); }
;     __device__ __forceinline__ void operator()(const f32x4 (&acc)[2][2][4][2], const pg8::Unit& u, int wr, int wc, int fr, int fq, LAS unsigned char* sp) const {
;     ...
;                 const int row = row0 + ai * 128 + m * 16; const float s = rsl[ai * 128 + m * 16];
; #pragma unroll
;                 for (int bj = 0; bj < 2; ++bj) {
;                     f32x4 v0 = acc[ai][bj][m][0] * s, v1 = acc[ai][bj][m][1] * s;
;                     const int col = colt + bj * 128 + cw0;
;                     if (act == 2) { const f32x4 b0 = *(const LAS f32x4*)(bsl + bj * 128 + cw0), b1 = *(const LAS f32x4*)(bsl + bj * 128 + cw0 + 4);
;                         v0 += b0; v1 += b1;
; #pragma unroll
;                         for (int j = 0; j < 4; ++j) { v0[j] = sigmoidf_(v0[j]); v1[j] = sigmoidf_(v1[j]); } }
;                     else if (act == 1) {
; #pragma unroll
;                         for (int j = 0; j < 4; ++j) { v0[j] = v0[j] * sigmoidf_(v0[j]); v1[j] = v1[j] * sigmoidf_(v1[j]); } }
;                     u32x4 w; w.x = cvt_pk_bf16(v0[0], v0[1]); w.y = cvt_pk_bf16(v0[2], v0[3]); w.z = cvt_pk_bf16(v1[0], v1[1]); w.w = cvt_pk_bf16(v1[2], v1[3]);
;                     *(u32x4*)(dst + (size_t)row * pitch + col) = w;
.LBB0_256:
	v_ashrrev_i32_e32 v163, 31, v202
	v_mul_lo_u32 v168, s63, v202
	v_mul_lo_u32 v163, s62, v163
	v_mad_u64_u32 v[166:167], s[26:27], s62, v202, 0
	v_add3_u32 v167, v167, v163, v168
	v_add_u32_e32 v0, s28, v199
	v_lshl_add_u64 v[166:167], v[166:167], 1, s[64:65]
	v_cvt_pk_bf16_f32 v168, v174, v176
	v_cvt_pk_bf16_f32 v169, v178, v180
	v_cvt_pk_bf16_f32 v170, v175, v177
	v_cvt_pk_bf16_f32 v171, v179, v181
	v_lshl_add_u64 v[166:167], v[0:1], 1, v[166:167]
	global_store_dwordx4 v[166:167], v[168:171], off nt
	v_mov_b32_e32 v165, v164
	v_pk_mul_f32 v[172:173], v[118:119], v[164:165]
	v_mov_b32_e32 v170, v164
	v_mov_b32_e32 v171, v164
	v_pk_mul_f32 v[168:169], v[120:121], v[170:171]
	v_pk_mul_f32 v[170:171], v[116:117], v[170:171]
	v_pk_mul_f32 v[164:165], v[114:115], v[164:165]
	s_cmp_gt_i32 s55, 1
	s_mov_b64 s[66:67], -1
	s_cbranch_scc0 .LBB0_258
	ds_read_b128 v[174:177], v161 offset:1536
	ds_read_b128 v[178:181], v161 offset:1552
	s_mov_b64 s[66:67], 0
	s_waitcnt lgkmcnt(0)
	v_pk_add_f32 v[182:183], v[168:169], v[176:177]
	v_pk_add_f32 v[176:177], v[172:173], v[174:175]
	v_pk_add_f32 v[180:181], v[170:171], v[180:181]
	v_pk_add_f32 v[178:179], v[164:165], v[178:179]
	v_mul_f32_e32 v174, 0xbfb8aa3b, v176
	v_mul_f32_e32 v175, 0xbfb8aa3b, v178
	v_mul_f32_e32 v176, 0xbfb8aa3b, v177
	v_mul_f32_e32 v177, 0xbfb8aa3b, v179
	v_mul_f32_e32 v178, 0xbfb8aa3b, v182
	v_mul_f32_e32 v179, 0xbfb8aa3b, v180
	v_mul_f32_e32 v180, 0xbfb8aa3b, v183
	v_mul_f32_e32 v181, 0xbfb8aa3b, v181
	v_exp_f32_e32 v174, v174
	v_exp_f32_e32 v175, v175
	v_exp_f32_e32 v176, v176
	v_exp_f32_e32 v177, v177
	v_exp_f32_e32 v178, v178
	v_exp_f32_e32 v179, v179
	v_exp_f32_e32 v180, v180
	v_exp_f32_e32 v181, v181
	v_add_f32_e32 v174, 1.0, v174
	v_add_f32_e32 v175, 1.0, v175
	v_add_f32_e32 v176, 1.0, v176
	v_add_f32_e32 v177, 1.0, v177
	v_add_f32_e32 v178, 1.0, v178
	v_add_f32_e32 v179, 1.0, v179
	v_add_f32_e32 v180, 1.0, v180
	v_add_f32_e32 v181, 1.0, v181
	v_rcp_f32_e32 v174, v174
	v_rcp_f32_e32 v175, v175
	v_rcp_f32_e32 v176, v176
	v_rcp_f32_e32 v177, v177
	v_rcp_f32_e32 v178, v178
	v_rcp_f32_e32 v179, v179
	v_rcp_f32_e32 v180, v180
	v_rcp_f32_e32 v181, v181

; #define LAS __attribute__((address_space(3)))
; __device__ __forceinline__ unsigned cvt_pk_bf16(float lo, float hi) { unsigned r; asm volatile("v_cvt_pk_bf16_f32 %0, %1, %2" : "=v"(r) : "v"(lo), "v"(hi)); return r; }
; __device__ __forceinline__ float sigmoidf_(float v) { return __builtin_amdgcn_rcpf(1.f + __expf(-v)); }
;     __device__ __forceinline__ void operator()(const f32x4 (&acc)[2][2][4][2], const pg8::Unit& u, int wr, int wc, int fr, int fq, LAS unsigned char* sp) const {
;     ...
;                 const int row = row0 + ai * 128 + m * 16; const float s = rsl[ai * 128 + m * 16];
; #pragma unroll
;                 for (int bj = 0; bj < 2; ++bj) {
;                     f32x4 v0 = acc[ai][bj][m][0] * s, v1 = acc[ai][bj][m][1] * s;
;                     const int col = colt + bj * 128 + cw0;
;                     if (act == 2) { const f32x4 b0 = *(const LAS f32x4*)(bsl + bj * 128 + cw0), b1 = *(const LAS f32x4*)(bsl + bj * 128 + cw0 + 4);
;                         v0 += b0; v1 += b1;
; #pragma unroll
;                         for (int j = 0; j < 4; ++j) { v0[j] = sigmoidf_(v0[j]); v1[j] = sigmoidf_(v1[j]); } }
;                     else if (act == 1) {
; #pragma unroll
;                         for (int j = 0; j < 4; ++j) { v0[j] = v0[j] * sigmoidf_(v0[j]); v1[j] = v1[j] * sigmoidf_(v1[j]); } }
;                     u32x4 w; w.x = cvt_pk_bf16(v0[0], v0[1]); w.y = cvt_pk_bf16(v0[2], v0[3]); w.z = cvt_pk_bf16(v1[0], v1[1]); w.w = cvt_pk_bf16(v1[2], v1[3]);
;                     *(u32x4*)(dst + (size_t)row * pitch + col) = w;
.LBB0_262:
	v_cvt_pk_bf16_f32 v168, v174, v176
	v_cvt_pk_bf16_f32 v169, v178, v180
	v_cvt_pk_bf16_f32 v170, v175, v177
	v_cvt_pk_bf16_f32 v171, v179, v181
	ds_read_b32 v164, v203 offset:64
	global_store_dwordx4 v[166:167], v[168:171], off offset:256 nt
	s_cmp_gt_i32 s55, 1
	s_mov_b64 s[66:67], -1
	s_waitcnt lgkmcnt(0)
	v_pk_mul_f32 v[168:169], v[112:113], v[164:165] op_sel_hi:[1,0]
	v_pk_mul_f32 v[172:173], v[110:111], v[164:165] op_sel_hi:[1,0]
	v_pk_mul_f32 v[166:167], v[108:109], v[164:165] op_sel_hi:[1,0]
	v_pk_mul_f32 v[170:171], v[106:107], v[164:165] op_sel_hi:[1,0]
	s_cbranch_scc0 .LBB0_264
	ds_read_b128 v[174:177], v161 offset:1024
	ds_read_b128 v[178:181], v161 offset:1040
	s_mov_b64 s[66:67], 0
	s_waitcnt lgkmcnt(0)
	v_pk_add_f32 v[182:183], v[168:169], v[176:177]
	v_pk_add_f32 v[176:177], v[172:173], v[174:175]
	v_pk_add_f32 v[178:179], v[170:171], v[178:179]
	v_mul_f32_e32 v165, 0xbfb8aa3b, v176
	v_exp_f32_e32 v165, v165
	v_pk_add_f32 v[180:181], v[166:167], v[180:181]
	v_add_f32_e32 v165, 1.0, v165
	v_rcp_f32_e32 v174, v165
	v_mul_f32_e32 v165, 0xbfb8aa3b, v178
	v_exp_f32_e32 v165, v165
	s_nop 0
	v_add_f32_e32 v165, 1.0, v165
	v_rcp_f32_e32 v175, v165
	v_mul_f32_e32 v165, 0xbfb8aa3b, v177
	v_exp_f32_e32 v165, v165
	s_nop 0
	v_add_f32_e32 v165, 1.0, v165
	v_rcp_f32_e32 v176, v165
	v_mul_f32_e32 v165, 0xbfb8aa3b, v179
	v_exp_f32_e32 v165, v165
	s_nop 0
	v_add_f32_e32 v165, 1.0, v165
	v_rcp_f32_e32 v177, v165
	v_mul_f32_e32 v165, 0xbfb8aa3b, v182
	v_exp_f32_e32 v165, v165
	s_nop 0
	v_add_f32_e32 v165, 1.0, v165
	v_rcp_f32_e32 v178, v165
	v_mul_f32_e32 v165, 0xbfb8aa3b, v180
	v_exp_f32_e32 v165, v165
	s_nop 0
	v_add_f32_e32 v165, 1.0, v165
	v_rcp_f32_e32 v179, v165
	v_mul_f32_e32 v165, 0xbfb8aa3b, v183
	v_exp_f32_e32 v165, v165
	s_nop 0
	v_add_f32_e32 v165, 1.0, v165
	v_rcp_f32_e32 v180, v165
	v_mul_f32_e32 v165, 0xbfb8aa3b, v181
	v_exp_f32_e32 v165, v165
	s_nop 0
	v_add_f32_e32 v165, 1.0, v165
	v_rcp_f32_e32 v181, v165

; #define LAS __attribute__((address_space(3)))
; __device__ __forceinline__ unsigned cvt_pk_bf16(float lo, float hi) { unsigned r; asm volatile("v_cvt_pk_bf16_f32 %0, %1, %2" : "=v"(r) : "v"(lo), "v"(hi)); return r; }
; __device__ __forceinline__ float sigmoidf_(float v) { return __builtin_amdgcn_rcpf(1.f + __expf(-v)); }
;     __device__ __forceinline__ void operator()(const f32x4 (&acc)[2][2][4][2], const pg8::Unit& u, int wr, int wc, int fr, int fq, LAS unsigned char* sp) const {
;     ...
;                 const int row = row0 + ai * 128 + m * 16; const float s = rsl[ai * 128 + m * 16];
; #pragma unroll
;                 for (int bj = 0; bj < 2; ++bj) {
;                     f32x4 v0 = acc[ai][bj][m][0] * s, v1 = acc[ai][bj][m][1] * s;
;                     const int col = colt + bj * 128 + cw0;
;                     if (act == 2) { const f32x4 b0 = *(const LAS f32x4*)(bsl + bj * 128 + cw0), b1 = *(const LAS f32x4*)(bsl + bj * 128 + cw0 + 4);
;                         v0 += b0; v1 += b1;
; #pragma unroll
;                         for (int j = 0; j < 4; ++j) { v0[j] = sigmoidf_(v0[j]); v1[j] = sigmoidf_(v1[j]); } }
;                     else if (act == 1) {
; #pragma unroll
;                         for (int j = 0; j < 4; ++j) { v0[j] = v0[j] * sigmoidf_(v0[j]); v1[j] = v1[j] * sigmoidf_(v1[j]); } }
;                     u32x4 w; w.x = cvt_pk_bf16(v0[0], v0[1]); w.y = cvt_pk_bf16(v0[2], v0[3]); w.z = cvt_pk_bf16(v1[0], v1[1]); w.w = cvt_pk_bf16(v1[2], v1[3]);
;                     *(u32x4*)(dst + (size_t)row * pitch + col) = w;
.LBB0_268:
	v_or_b32_e32 v166, 16, v202
	v_mul_lo_u32 v168, s63, v166
	v_mad_u64_u32 v[166:167], s[26:27], s62, v166, 0
	v_add3_u32 v167, v167, v163, v168
	v_lshl_add_u64 v[166:167], v[166:167], 1, s[64:65]
	v_cvt_pk_bf16_f32 v168, v174, v176
	v_cvt_pk_bf16_f32 v169, v178, v180
	v_cvt_pk_bf16_f32 v170, v175, v177
	v_cvt_pk_bf16_f32 v171, v179, v181
	v_lshl_add_u64 v[166:167], v[0:1], 1, v[166:167]
	global_store_dwordx4 v[166:167], v[168:171], off nt
	v_mov_b32_e32 v165, v164
	v_pk_mul_f32 v[172:173], v[102:103], v[164:165]
	v_mov_b32_e32 v170, v164
	v_mov_b32_e32 v171, v164
	v_pk_mul_f32 v[168:169], v[104:105], v[170:171]
	v_pk_mul_f32 v[170:171], v[100:101], v[170:171]
	v_pk_mul_f32 v[164:165], v[98:99], v[164:165]
	s_cmp_gt_i32 s55, 1
	s_mov_b64 s[66:67], -1
	s_cbranch_scc0 .LBB0_270
	ds_read_b128 v[174:177], v161 offset:1536
	ds_read_b128 v[178:181], v161 offset:1552
	s_mov_b64 s[66:67], 0
	s_waitcnt lgkmcnt(0)
	v_pk_add_f32 v[182:183], v[168:169], v[176:177]
	v_pk_add_f32 v[176:177], v[172:173], v[174:175]
	v_pk_add_f32 v[180:181], v[170:171], v[180:181]
	v_pk_add_f32 v[178:179], v[164:165], v[178:179]
	v_mul_f32_e32 v174, 0xbfb8aa3b, v176
	v_mul_f32_e32 v175, 0xbfb8aa3b, v178
	v_mul_f32_e32 v176, 0xbfb8aa3b, v177
	v_mul_f32_e32 v177, 0xbfb8aa3b, v179
	v_mul_f32_e32 v178, 0xbfb8aa3b, v182
	v_mul_f32_e32 v179, 0xbfb8aa3b, v180
	v_mul_f32_e32 v180, 0xbfb8aa3b, v183
	v_mul_f32_e32 v181, 0xbfb8aa3b, v181
	v_exp_f32_e32 v174, v174
	v_exp_f32_e32 v175, v175
	v_exp_f32_e32 v176, v176
	v_exp_f32_e32 v177, v177
	v_exp_f32_e32 v178, v178
	v_exp_f32_e32 v179, v179
	v_exp_f32_e32 v180, v180
	v_exp_f32_e32 v181, v181
	v_add_f32_e32 v174, 1.0, v174
	v_add_f32_e32 v175, 1.0, v175
	v_add_f32_e32 v176, 1.0, v176
	v_add_f32_e32 v177, 1.0, v177
	v_add_f32_e32 v178, 1.0, v178
	v_add_f32_e32 v179, 1.0, v179
	v_add_f32_e32 v180, 1.0, v180
	v_add_f32_e32 v181, 1.0, v181
	v_rcp_f32_e32 v174, v174
	v_rcp_f32_e32 v175, v175
	v_rcp_f32_e32 v176, v176
	v_rcp_f32_e32 v177, v177
	v_rcp_f32_e32 v178, v178
	v_rcp_f32_e32 v179, v179
	v_rcp_f32_e32 v180, v180
	v_rcp_f32_e32 v181, v181

; #define LAS __attribute__((address_space(3)))
; __device__ __forceinline__ unsigned cvt_pk_bf16(float lo, float hi) { unsigned r; asm volatile("v_cvt_pk_bf16_f32 %0, %1, %2" : "=v"(r) : "v"(lo), "v"(hi)); return r; }
; __device__ __forceinline__ float sigmoidf_(float v) { return __builtin_amdgcn_rcpf(1.f + __expf(-v)); }
;     __device__ __forceinline__ void operator()(const f32x4 (&acc)[2][2][4][2], const pg8::Unit& u, int wr, int wc, int fr, int fq, LAS unsigned char* sp) const {
;     ...
;                 const int row = row0 + ai * 128 + m * 16; const float s = rsl[ai * 128 + m * 16];
; #pragma unroll
;                 for (int bj = 0; bj < 2; ++bj) {
;                     f32x4 v0 = acc[ai][bj][m][0] * s, v1 = acc[ai][bj][m][1] * s;
;                     const int col = colt + bj * 128 + cw0;
;                     if (act == 2) { const f32x4 b0 = *(const LAS f32x4*)(bsl + bj * 128 + cw0), b1 = *(const LAS f32x4*)(bsl + bj * 128 + cw0 + 4);
;                         v0 += b0; v1 += b1;
; #pragma unroll
;                         for (int j = 0; j < 4; ++j) { v0[j] = sigmoidf_(v0[j]); v1[j] = sigmoidf_(v1[j]); } }
;                     else if (act == 1) {
; #pragma unroll
;                         for (int j = 0; j < 4; ++j) { v0[j] = v0[j] * sigmoidf_(v0[j]); v1[j] = v1[j] * sigmoidf_(v1[j]); } }
;                     u32x4 w; w.x = cvt_pk_bf16(v0[0], v0[1]); w.y = cvt_pk_bf16(v0[2], v0[3]); w.z = cvt_pk_bf16(v1[0], v1[1]); w.w = cvt_pk_bf16(v1[2], v1[3]);
;                     *(u32x4*)(dst + (size_t)row * pitch + col) = w;
.LBB0_274:
	v_cvt_pk_bf16_f32 v168, v174, v176
	v_cvt_pk_bf16_f32 v169, v178, v180
	v_cvt_pk_bf16_f32 v170, v175, v177
	v_cvt_pk_bf16_f32 v171, v179, v181
	ds_read_b32 v164, v203 offset:128
	global_store_dwordx4 v[166:167], v[168:171], off offset:256 nt
	s_cmp_gt_i32 s55, 1
	s_mov_b64 s[66:67], -1
	s_waitcnt lgkmcnt(0)
	v_pk_mul_f32 v[168:169], v[96:97], v[164:165] op_sel_hi:[1,0]
	v_pk_mul_f32 v[172:173], v[94:95], v[164:165] op_sel_hi:[1,0]
	v_pk_mul_f32 v[166:167], v[92:93], v[164:165] op_sel_hi:[1,0]
	v_pk_mul_f32 v[170:171], v[90:91], v[164:165] op_sel_hi:[1,0]
	s_cbranch_scc0 .LBB0_276
	ds_read_b128 v[174:177], v161 offset:1024
	ds_read_b128 v[178:181], v161 offset:1040
	s_mov_b64 s[66:67], 0
	s_waitcnt lgkmcnt(0)
	v_pk_add_f32 v[182:183], v[168:169], v[176:177]
	v_pk_add_f32 v[176:177], v[172:173], v[174:175]
	v_pk_add_f32 v[178:179], v[170:171], v[178:179]
	v_mul_f32_e32 v165, 0xbfb8aa3b, v176
	v_exp_f32_e32 v165, v165
	v_pk_add_f32 v[180:181], v[166:167], v[180:181]
	v_add_f32_e32 v165, 1.0, v165
	v_rcp_f32_e32 v174, v165
	v_mul_f32_e32 v165, 0xbfb8aa3b, v178
	v_exp_f32_e32 v165, v165
	s_nop 0
	v_add_f32_e32 v165, 1.0, v165
	v_rcp_f32_e32 v175, v165
	v_mul_f32_e32 v165, 0xbfb8aa3b, v177
	v_exp_f32_e32 v165, v165
	s_nop 0
	v_add_f32_e32 v165, 1.0, v165
	v_rcp_f32_e32 v176, v165
	v_mul_f32_e32 v165, 0xbfb8aa3b, v179
	v_exp_f32_e32 v165, v165
	s_nop 0
	v_add_f32_e32 v165, 1.0, v165
	v_rcp_f32_e32 v177, v165
	v_mul_f32_e32 v165, 0xbfb8aa3b, v182
	v_exp_f32_e32 v165, v165
	s_nop 0
	v_add_f32_e32 v165, 1.0, v165
	v_rcp_f32_e32 v178, v165
	v_mul_f32_e32 v165, 0xbfb8aa3b, v180
	v_exp_f32_e32 v165, v165
	s_nop 0
	v_add_f32_e32 v165, 1.0, v165
	v_rcp_f32_e32 v179, v165
	v_mul_f32_e32 v165, 0xbfb8aa3b, v183
	v_exp_f32_e32 v165, v165
	s_nop 0
	v_add_f32_e32 v165, 1.0, v165
	v_rcp_f32_e32 v180, v165
	v_mul_f32_e32 v165, 0xbfb8aa3b, v181
	v_exp_f32_e32 v165, v165
	s_nop 0
	v_add_f32_e32 v165, 1.0, v165
	v_rcp_f32_e32 v181, v165

; #define LAS __attribute__((address_space(3)))
; __device__ __forceinline__ unsigned cvt_pk_bf16(float lo, float hi) { unsigned r; asm volatile("v_cvt_pk_bf16_f32 %0, %1, %2" : "=v"(r) : "v"(lo), "v"(hi)); return r; }
; __device__ __forceinline__ float sigmoidf_(float v) { return __builtin_amdgcn_rcpf(1.f + __expf(-v)); }
;     __device__ __forceinline__ void operator()(const f32x4 (&acc)[2][2][4][2], const pg8::Unit& u, int wr, int wc, int fr, int fq, LAS unsigned char* sp) const {
;     ...
;                 const int row = row0 + ai * 128 + m * 16; const float s = rsl[ai * 128 + m * 16];
; #pragma unroll
;                 for (int bj = 0; bj < 2; ++bj) {
;                     f32x4 v0 = acc[ai][bj][m][0] * s, v1 = acc[ai][bj][m][1] * s;
;                     const int col = colt + bj * 128 + cw0;
;                     if (act == 2) { const f32x4 b0 = *(const LAS f32x4*)(bsl + bj * 128 + cw0), b1 = *(const LAS f32x4*)(bsl + bj * 128 + cw0 + 4);
;                         v0 += b0; v1 += b1;
; #pragma unroll
;                         for (int j = 0; j < 4; ++j) { v0[j] = sigmoidf_(v0[j]); v1[j] = sigmoidf_(v1[j]); } }
;                     else if (act == 1) {
; #pragma unroll
;                         for (int j = 0; j < 4; ++j) { v0[j] = v0[j] * sigmoidf_(v0[j]); v1[j] = v1[j] * sigmoidf_(v1[j]); } }
;                     u32x4 w; w.x = cvt_pk_bf16(v0[0], v0[1]); w.y = cvt_pk_bf16(v0[2], v0[3]); w.z = cvt_pk_bf16(v1[0], v1[1]); w.w = cvt_pk_bf16(v1[2], v1[3]);
;                     *(u32x4*)(dst + (size_t)row * pitch + col) = w;
.LBB0_280:
	v_or_b32_e32 v166, 32, v202
	v_mul_lo_u32 v168, s63, v166
	v_mad_u64_u32 v[166:167], s[26:27], s62, v166, 0
	v_add3_u32 v167, v167, v163, v168
	v_lshl_add_u64 v[166:167], v[166:167], 1, s[64:65]
	v_cvt_pk_bf16_f32 v168, v174, v176
	v_cvt_pk_bf16_f32 v169, v178, v180
	v_cvt_pk_bf16_f32 v170, v175, v177
	v_cvt_pk_bf16_f32 v171, v179, v181
	v_lshl_add_u64 v[166:167], v[0:1], 1, v[166:167]
	global_store_dwordx4 v[166:167], v[168:171], off nt
	v_mov_b32_e32 v165, v164
	v_pk_mul_f32 v[172:173], v[86:87], v[164:165]
	v_mov_b32_e32 v170, v164
	v_mov_b32_e32 v171, v164
	v_pk_mul_f32 v[168:169], v[88:89], v[170:171]
	v_pk_mul_f32 v[170:171], v[84:85], v[170:171]
	v_pk_mul_f32 v[164:165], v[82:83], v[164:165]
	s_cmp_gt_i32 s55, 1
	s_mov_b64 s[66:67], -1
	s_cbranch_scc0 .LBB0_282
	ds_read_b128 v[174:177], v161 offset:1536
	ds_read_b128 v[178:181], v161 offset:1552
	s_mov_b64 s[66:67], 0
	s_waitcnt lgkmcnt(0)
	v_pk_add_f32 v[182:183], v[168:169], v[176:177]
	v_pk_add_f32 v[176:177], v[172:173], v[174:175]
	v_pk_add_f32 v[180:181], v[170:171], v[180:181]
	v_pk_add_f32 v[178:179], v[164:165], v[178:179]
	v_mul_f32_e32 v174, 0xbfb8aa3b, v176
	v_mul_f32_e32 v175, 0xbfb8aa3b, v178
	v_mul_f32_e32 v176, 0xbfb8aa3b, v177
	v_mul_f32_e32 v177, 0xbfb8aa3b, v179
	v_mul_f32_e32 v178, 0xbfb8aa3b, v182
	v_mul_f32_e32 v179, 0xbfb8aa3b, v180
	v_mul_f32_e32 v180, 0xbfb8aa3b, v183
	v_mul_f32_e32 v181, 0xbfb8aa3b, v181
	v_exp_f32_e32 v174, v174
	v_exp_f32_e32 v175, v175
	v_exp_f32_e32 v176, v176
	v_exp_f32_e32 v177, v177
	v_exp_f32_e32 v178, v178
	v_exp_f32_e32 v179, v179
	v_exp_f32_e32 v180, v180
	v_exp_f32_e32 v181, v181
	v_add_f32_e32 v174, 1.0, v174
	v_add_f32_e32 v175, 1.0, v175
	v_add_f32_e32 v176, 1.0, v176
	v_add_f32_e32 v177, 1.0, v177
	v_add_f32_e32 v178, 1.0, v178
	v_add_f32_e32 v179, 1.0, v179
	v_add_f32_e32 v180, 1.0, v180
	v_add_f32_e32 v181, 1.0, v181
	v_rcp_f32_e32 v174, v174
	v_rcp_f32_e32 v175, v175
	v_rcp_f32_e32 v176, v176
	v_rcp_f32_e32 v177, v177
	v_rcp_f32_e32 v178, v178
	v_rcp_f32_e32 v179, v179
	v_rcp_f32_e32 v180, v180
	v_rcp_f32_e32 v181, v181

; #define LAS __attribute__((address_space(3)))
; __device__ __forceinline__ unsigned cvt_pk_bf16(float lo, float hi) { unsigned r; asm volatile("v_cvt_pk_bf16_f32 %0, %1, %2" : "=v"(r) : "v"(lo), "v"(hi)); return r; }
; __device__ __forceinline__ float sigmoidf_(float v) { return __builtin_amdgcn_rcpf(1.f + __expf(-v)); }
;     __device__ __forceinline__ void operator()(const f32x4 (&acc)[2][2][4][2], const pg8::Unit& u, int wr, int wc, int fr, int fq, LAS unsigned char* sp) const {
;     ...
;                 const int row = row0 + ai * 128 + m * 16; const float s = rsl[ai * 128 + m * 16];
; #pragma unroll
;                 for (int bj = 0; bj < 2; ++bj) {
;                     f32x4 v0 = acc[ai][bj][m][0] * s, v1 = acc[ai][bj][m][1] * s;
;                     const int col = colt + bj * 128 + cw0;
;                     if (act == 2) { const f32x4 b0 = *(const LAS f32x4*)(bsl + bj * 128 + cw0), b1 = *(const LAS f32x4*)(bsl + bj * 128 + cw0 + 4);
;                         v0 += b0; v1 += b1;
; #pragma unroll
;                         for (int j = 0; j < 4; ++j) { v0[j] = sigmoidf_(v0[j]); v1[j] = sigmoidf_(v1[j]); } }
;                     else if (act == 1) {
; #pragma unroll
;                         for (int j = 0; j < 4; ++j) { v0[j] = v0[j] * sigmoidf_(v0[j]); v1[j] = v1[j] * sigmoidf_(v1[j]); } }
;                     u32x4 w; w.x = cvt_pk_bf16(v0[0], v0[1]); w.y = cvt_pk_bf16(v0[2], v0[3]); w.z = cvt_pk_bf16(v1[0], v1[1]); w.w = cvt_pk_bf16(v1[2], v1[3]);
;                     *(u32x4*)(dst + (size_t)row * pitch + col) = w;
.LBB0_286:
	v_cvt_pk_bf16_f32 v168, v174, v176
	v_cvt_pk_bf16_f32 v169, v178, v180
	v_cvt_pk_bf16_f32 v170, v175, v177
	v_cvt_pk_bf16_f32 v171, v179, v181
	ds_read_b32 v164, v203 offset:192
	global_store_dwordx4 v[166:167], v[168:171], off offset:256 nt
	s_cmp_gt_i32 s55, 1
	s_mov_b64 s[66:67], -1
	s_waitcnt lgkmcnt(0)
	v_pk_mul_f32 v[168:169], v[80:81], v[164:165] op_sel_hi:[1,0]
	v_pk_mul_f32 v[172:173], v[78:79], v[164:165] op_sel_hi:[1,0]
	v_pk_mul_f32 v[166:167], v[76:77], v[164:165] op_sel_hi:[1,0]
	v_pk_mul_f32 v[170:171], v[74:75], v[164:165] op_sel_hi:[1,0]
	s_cbranch_scc0 .LBB0_288
	ds_read_b128 v[174:177], v161 offset:1024
	ds_read_b128 v[178:181], v161 offset:1040
	s_mov_b64 s[66:67], 0
	s_waitcnt lgkmcnt(0)
	v_pk_add_f32 v[182:183], v[168:169], v[176:177]
	v_pk_add_f32 v[176:177], v[172:173], v[174:175]
	v_pk_add_f32 v[178:179], v[170:171], v[178:179]
	v_mul_f32_e32 v165, 0xbfb8aa3b, v176
	v_exp_f32_e32 v165, v165
	v_pk_add_f32 v[180:181], v[166:167], v[180:181]
	v_add_f32_e32 v165, 1.0, v165
	v_rcp_f32_e32 v174, v165
	v_mul_f32_e32 v165, 0xbfb8aa3b, v178
	v_exp_f32_e32 v165, v165
	s_nop 0
	v_add_f32_e32 v165, 1.0, v165
	v_rcp_f32_e32 v175, v165
	v_mul_f32_e32 v165, 0xbfb8aa3b, v177
	v_exp_f32_e32 v165, v165
	s_nop 0
	v_add_f32_e32 v165, 1.0, v165
	v_rcp_f32_e32 v176, v165
	v_mul_f32_e32 v165, 0xbfb8aa3b, v179
	v_exp_f32_e32 v165, v165
	s_nop 0
	v_add_f32_e32 v165, 1.0, v165
	v_rcp_f32_e32 v177, v165
	v_mul_f32_e32 v165, 0xbfb8aa3b, v182
	v_exp_f32_e32 v165, v165
	s_nop 0
	v_add_f32_e32 v165, 1.0, v165
	v_rcp_f32_e32 v178, v165
	v_mul_f32_e32 v165, 0xbfb8aa3b, v180
	v_exp_f32_e32 v165, v165
	s_nop 0
	v_add_f32_e32 v165, 1.0, v165
	v_rcp_f32_e32 v179, v165
	v_mul_f32_e32 v165, 0xbfb8aa3b, v183
	v_exp_f32_e32 v165, v165
	s_nop 0
	v_add_f32_e32 v165, 1.0, v165
	v_rcp_f32_e32 v180, v165
	v_mul_f32_e32 v165, 0xbfb8aa3b, v181
	v_exp_f32_e32 v165, v165
	s_nop 0
	v_add_f32_e32 v165, 1.0, v165
	v_rcp_f32_e32 v181, v165

; #define LAS __attribute__((address_space(3)))
; __device__ __forceinline__ unsigned cvt_pk_bf16(float lo, float hi) { unsigned r; asm volatile("v_cvt_pk_bf16_f32 %0, %1, %2" : "=v"(r) : "v"(lo), "v"(hi)); return r; }
; __device__ __forceinline__ float sigmoidf_(float v) { return __builtin_amdgcn_rcpf(1.f + __expf(-v)); }
;     __device__ __forceinline__ void operator()(const f32x4 (&acc)[2][2][4][2], const pg8::Unit& u, int wr, int wc, int fr, int fq, LAS unsigned char* sp) const {
;     ...
;                 const int row = row0 + ai * 128 + m * 16; const float s = rsl[ai * 128 + m * 16];
; #pragma unroll
;                 for (int bj = 0; bj < 2; ++bj) {
;                     f32x4 v0 = acc[ai][bj][m][0] * s, v1 = acc[ai][bj][m][1] * s;
;                     const int col = colt + bj * 128 + cw0;
;                     if (act == 2) { const f32x4 b0 = *(const LAS f32x4*)(bsl + bj * 128 + cw0), b1 = *(const LAS f32x4*)(bsl + bj * 128 + cw0 + 4);
;                         v0 += b0; v1 += b1;
; #pragma unroll
;                         for (int j = 0; j < 4; ++j) { v0[j] = sigmoidf_(v0[j]); v1[j] = sigmoidf_(v1[j]); } }
;                     else if (act == 1) {
; #pragma unroll
;                         for (int j = 0; j < 4; ++j) { v0[j] = v0[j] * sigmoidf_(v0[j]); v1[j] = v1[j] * sigmoidf_(v1[j]); } }
;                     u32x4 w; w.x = cvt_pk_bf16(v0[0], v0[1]); w.y = cvt_pk_bf16(v0[2], v0[3]); w.z = cvt_pk_bf16(v1[0], v1[1]); w.w = cvt_pk_bf16(v1[2], v1[3]);
;                     *(u32x4*)(dst + (size_t)row * pitch + col) = w;
.LBB0_292:
	v_or_b32_e32 v166, 48, v202
	v_mul_lo_u32 v168, s63, v166
	v_mad_u64_u32 v[166:167], s[26:27], s62, v166, 0
	v_add3_u32 v167, v167, v163, v168
	v_lshl_add_u64 v[166:167], v[166:167], 1, s[64:65]
	v_cvt_pk_bf16_f32 v168, v174, v176
	v_cvt_pk_bf16_f32 v169, v178, v180
	v_cvt_pk_bf16_f32 v170, v175, v177
	v_cvt_pk_bf16_f32 v171, v179, v181
	v_lshl_add_u64 v[166:167], v[0:1], 1, v[166:167]
	global_store_dwordx4 v[166:167], v[168:171], off nt
	v_mov_b32_e32 v165, v164
	v_pk_mul_f32 v[172:173], v[70:71], v[164:165]
	v_mov_b32_e32 v170, v164
	v_mov_b32_e32 v171, v164
	v_pk_mul_f32 v[168:169], v[72:73], v[170:171]
	v_pk_mul_f32 v[170:171], v[68:69], v[170:171]
	v_pk_mul_f32 v[164:165], v[66:67], v[164:165]
	s_cmp_gt_i32 s55, 1
	s_mov_b64 s[66:67], -1
	s_cbranch_scc0 .LBB0_294
	ds_read_b128 v[174:177], v161 offset:1536
	ds_read_b128 v[178:181], v161 offset:1552
	s_mov_b64 s[66:67], 0
	s_waitcnt lgkmcnt(0)
	v_pk_add_f32 v[182:183], v[168:169], v[176:177]
	v_pk_add_f32 v[174:175], v[172:173], v[174:175]
	v_pk_add_f32 v[180:181], v[170:171], v[180:181]
	v_pk_add_f32 v[176:177], v[164:165], v[178:179]
	v_mul_f32_e32 v163, 0xbfb8aa3b, v174
	v_mul_f32_e32 v174, 0xbfb8aa3b, v176
	v_mul_f32_e32 v175, 0xbfb8aa3b, v175
	v_mul_f32_e32 v176, 0xbfb8aa3b, v177
	v_mul_f32_e32 v177, 0xbfb8aa3b, v182
	v_mul_f32_e32 v178, 0xbfb8aa3b, v180
	v_mul_f32_e32 v179, 0xbfb8aa3b, v183
	v_mul_f32_e32 v180, 0xbfb8aa3b, v181
	v_exp_f32_e32 v163, v163
	v_exp_f32_e32 v174, v174
	v_exp_f32_e32 v175, v175
	v_exp_f32_e32 v176, v176
	v_exp_f32_e32 v177, v177
	v_exp_f32_e32 v178, v178
	v_exp_f32_e32 v179, v179
	v_exp_f32_e32 v180, v180
	v_add_f32_e32 v163, 1.0, v163
	v_add_f32_e32 v174, 1.0, v174
	v_add_f32_e32 v175, 1.0, v175
	v_add_f32_e32 v176, 1.0, v176
	v_add_f32_e32 v177, 1.0, v177
	v_add_f32_e32 v178, 1.0, v178
	v_add_f32_e32 v179, 1.0, v179
	v_add_f32_e32 v180, 1.0, v180
	v_rcp_f32_e32 v163, v163
	v_rcp_f32_e32 v174, v174
	v_rcp_f32_e32 v175, v175
	v_rcp_f32_e32 v176, v176
	v_rcp_f32_e32 v177, v177
	v_rcp_f32_e32 v178, v178
	v_rcp_f32_e32 v179, v179
	v_rcp_f32_e32 v180, v180

; #define LAS __attribute__((address_space(3)))
; __device__ __forceinline__ unsigned cvt_pk_bf16(float lo, float hi) { unsigned r; asm volatile("v_cvt_pk_bf16_f32 %0, %1, %2" : "=v"(r) : "v"(lo), "v"(hi)); return r; }
; __device__ __forceinline__ float sigmoidf_(float v) { return __builtin_amdgcn_rcpf(1.f + __expf(-v)); }
;     __device__ __forceinline__ void operator()(const f32x4 (&acc)[2][2][4][2], const pg8::Unit& u, int wr, int wc, int fr, int fq, LAS unsigned char* sp) const {
;     ...
;                 const int row = row0 + ai * 128 + m * 16; const float s = rsl[ai * 128 + m * 16];
; #pragma unroll
;                 for (int bj = 0; bj < 2; ++bj) {
;                     f32x4 v0 = acc[ai][bj][m][0] * s, v1 = acc[ai][bj][m][1] * s;
;                     const int col = colt + bj * 128 + cw0;
;                     if (act == 2) { const f32x4 b0 = *(const LAS f32x4*)(bsl + bj * 128 + cw0), b1 = *(const LAS f32x4*)(bsl + bj * 128 + cw0 + 4);
;                         v0 += b0; v1 += b1;
; #pragma unroll
;                         for (int j = 0; j < 4; ++j) { v0[j] = sigmoidf_(v0[j]); v1[j] = sigmoidf_(v1[j]); } }
;                     else if (act == 1) {
; #pragma unroll
;                         for (int j = 0; j < 4; ++j) { v0[j] = v0[j] * sigmoidf_(v0[j]); v1[j] = v1[j] * sigmoidf_(v1[j]); } }
;                     u32x4 w; w.x = cvt_pk_bf16(v0[0], v0[1]); w.y = cvt_pk_bf16(v0[2], v0[3]); w.z = cvt_pk_bf16(v1[0], v1[1]); w.w = cvt_pk_bf16(v1[2], v1[3]);
;                     *(u32x4*)(dst + (size_t)row * pitch + col) = w;
.LBB0_298:
	v_cvt_pk_bf16_f32 v168, v163, v175
	v_cvt_pk_bf16_f32 v169, v177, v179
	v_cvt_pk_bf16_f32 v170, v174, v176
	v_cvt_pk_bf16_f32 v171, v178, v180
	ds_read_b32 v164, v203 offset:512
	global_store_dwordx4 v[166:167], v[168:171], off offset:256 nt
	s_cmp_gt_i32 s55, 1
	s_mov_b64 s[66:67], -1
	s_waitcnt lgkmcnt(0)
	v_pk_mul_f32 v[168:169], v[64:65], v[164:165] op_sel_hi:[1,0]
	v_pk_mul_f32 v[172:173], v[62:63], v[164:165] op_sel_hi:[1,0]
	v_pk_mul_f32 v[166:167], v[60:61], v[164:165] op_sel_hi:[1,0]
	v_pk_mul_f32 v[170:171], v[58:59], v[164:165] op_sel_hi:[1,0]
	s_cbranch_scc0 .LBB0_300
	ds_read_b128 v[174:177], v161 offset:1024
	ds_read_b128 v[178:181], v161 offset:1040
	s_mov_b64 s[66:67], 0
	s_waitcnt lgkmcnt(0)
	v_pk_add_f32 v[182:183], v[168:169], v[176:177]
	v_pk_add_f32 v[176:177], v[170:171], v[178:179]
	v_pk_add_f32 v[174:175], v[172:173], v[174:175]
	v_mul_f32_e32 v165, 0xbfb8aa3b, v176
	v_exp_f32_e32 v165, v165
	v_mul_f32_e32 v163, 0xbfb8aa3b, v174
	v_pk_add_f32 v[180:181], v[166:167], v[180:181]
	v_exp_f32_e32 v163, v163
	v_add_f32_e32 v165, 1.0, v165
	v_rcp_f32_e32 v174, v165
	v_mul_f32_e32 v165, 0xbfb8aa3b, v175
	v_exp_f32_e32 v165, v165
	v_add_f32_e32 v163, 1.0, v163
	v_rcp_f32_e32 v163, v163
	v_add_f32_e32 v165, 1.0, v165
	v_rcp_f32_e32 v175, v165
	v_mul_f32_e32 v165, 0xbfb8aa3b, v177
	v_exp_f32_e32 v165, v165
	s_nop 0
	v_add_f32_e32 v165, 1.0, v165
	v_rcp_f32_e32 v176, v165
	v_mul_f32_e32 v165, 0xbfb8aa3b, v182
	v_exp_f32_e32 v165, v165
	s_nop 0
	v_add_f32_e32 v165, 1.0, v165
	v_rcp_f32_e32 v177, v165
	v_mul_f32_e32 v165, 0xbfb8aa3b, v180
	v_exp_f32_e32 v165, v165
	s_nop 0
	v_add_f32_e32 v165, 1.0, v165
	v_rcp_f32_e32 v178, v165
	v_mul_f32_e32 v165, 0xbfb8aa3b, v183
	v_exp_f32_e32 v165, v165
	s_nop 0
	v_add_f32_e32 v165, 1.0, v165
	v_rcp_f32_e32 v179, v165
	v_mul_f32_e32 v165, 0xbfb8aa3b, v181
	v_exp_f32_e32 v165, v165
	s_nop 0
	v_add_f32_e32 v165, 1.0, v165
	v_rcp_f32_e32 v180, v165

; #define LAS __attribute__((address_space(3)))
; __device__ __forceinline__ unsigned cvt_pk_bf16(float lo, float hi) { unsigned r; asm volatile("v_cvt_pk_bf16_f32 %0, %1, %2" : "=v"(r) : "v"(lo), "v"(hi)); return r; }
; __device__ __forceinline__ float sigmoidf_(float v) { return __builtin_amdgcn_rcpf(1.f + __expf(-v)); }
;     __device__ __forceinline__ void operator()(const f32x4 (&acc)[2][2][4][2], const pg8::Unit& u, int wr, int wc, int fr, int fq, LAS unsigned char* sp) const {
;     ...
;                 const int row = row0 + ai * 128 + m * 16; const float s = rsl[ai * 128 + m * 16];
; #pragma unroll
;                 for (int bj = 0; bj < 2; ++bj) {
;                     f32x4 v0 = acc[ai][bj][m][0] * s, v1 = acc[ai][bj][m][1] * s;
;                     const int col = colt + bj * 128 + cw0;
;                     if (act == 2) { const f32x4 b0 = *(const LAS f32x4*)(bsl + bj * 128 + cw0), b1 = *(const LAS f32x4*)(bsl + bj * 128 + cw0 + 4);
;                         v0 += b0; v1 += b1;
; #pragma unroll
;                         for (int j = 0; j < 4; ++j) { v0[j] = sigmoidf_(v0[j]); v1[j] = sigmoidf_(v1[j]); } }
;                     else if (act == 1) {
; #pragma unroll
;                         for (int j = 0; j < 4; ++j) { v0[j] = v0[j] * sigmoidf_(v0[j]); v1[j] = v1[j] * sigmoidf_(v1[j]); } }
;                     u32x4 w; w.x = cvt_pk_bf16(v0[0], v0[1]); w.y = cvt_pk_bf16(v0[2], v0[3]); w.z = cvt_pk_bf16(v1[0], v1[1]); w.w = cvt_pk_bf16(v1[2], v1[3]);
;                     *(u32x4*)(dst + (size_t)row * pitch + col) = w;
.LBB0_304:
	v_add_u32_e32 v166, 0x80, v202
	v_ashrrev_i32_e32 v167, 31, v166
	v_mul_lo_u32 v168, s62, v167
	v_mul_lo_u32 v169, s63, v166
	v_mad_u64_u32 v[166:167], s[26:27], s62, v166, 0
	v_add3_u32 v167, v167, v168, v169
	v_lshl_add_u64 v[166:167], v[166:167], 1, s[64:65]
	v_cvt_pk_bf16_f32 v168, v163, v175
	v_cvt_pk_bf16_f32 v169, v177, v179
	v_cvt_pk_bf16_f32 v170, v174, v176
	v_cvt_pk_bf16_f32 v171, v178, v180
	v_lshl_add_u64 v[166:167], v[0:1], 1, v[166:167]
	global_store_dwordx4 v[166:167], v[168:171], off nt
	v_mov_b32_e32 v165, v164
	v_pk_mul_f32 v[172:173], v[54:55], v[164:165]
	v_mov_b32_e32 v170, v164
	v_mov_b32_e32 v171, v164
	v_pk_mul_f32 v[168:169], v[56:57], v[170:171]
	v_pk_mul_f32 v[170:171], v[52:53], v[170:171]
	v_pk_mul_f32 v[164:165], v[50:51], v[164:165]
	s_cmp_gt_i32 s55, 1
	s_mov_b64 s[66:67], -1
	s_cbranch_scc0 .LBB0_306
	ds_read_b128 v[174:177], v161 offset:1536
	ds_read_b128 v[178:181], v161 offset:1552
	s_mov_b64 s[66:67], 0
	s_waitcnt lgkmcnt(0)
	v_pk_add_f32 v[182:183], v[168:169], v[176:177]
	v_pk_add_f32 v[174:175], v[172:173], v[174:175]
	v_pk_add_f32 v[180:181], v[170:171], v[180:181]
	v_pk_add_f32 v[176:177], v[164:165], v[178:179]
	v_mul_f32_e32 v163, 0xbfb8aa3b, v174
	v_mul_f32_e32 v174, 0xbfb8aa3b, v176
	v_mul_f32_e32 v175, 0xbfb8aa3b, v175
	v_mul_f32_e32 v176, 0xbfb8aa3b, v177
	v_mul_f32_e32 v177, 0xbfb8aa3b, v182
	v_mul_f32_e32 v178, 0xbfb8aa3b, v180
	v_mul_f32_e32 v179, 0xbfb8aa3b, v183
	v_mul_f32_e32 v180, 0xbfb8aa3b, v181
	v_exp_f32_e32 v163, v163
	v_exp_f32_e32 v174, v174
	v_exp_f32_e32 v175, v175
	v_exp_f32_e32 v176, v176
	v_exp_f32_e32 v177, v177
	v_exp_f32_e32 v178, v178
	v_exp_f32_e32 v179, v179
	v_exp_f32_e32 v180, v180
	v_add_f32_e32 v163, 1.0, v163
	v_add_f32_e32 v174, 1.0, v174
	v_add_f32_e32 v175, 1.0, v175
	v_add_f32_e32 v176, 1.0, v176
	v_add_f32_e32 v177, 1.0, v177
	v_add_f32_e32 v178, 1.0, v178
	v_add_f32_e32 v179, 1.0, v179
	v_add_f32_e32 v180, 1.0, v180
	v_rcp_f32_e32 v163, v163
	v_rcp_f32_e32 v174, v174
	v_rcp_f32_e32 v175, v175
	v_rcp_f32_e32 v176, v176
	v_rcp_f32_e32 v177, v177
	v_rcp_f32_e32 v178, v178
	v_rcp_f32_e32 v179, v179
	v_rcp_f32_e32 v180, v180

; #define LAS __attribute__((address_space(3)))
; __device__ __forceinline__ unsigned cvt_pk_bf16(float lo, float hi) { unsigned r; asm volatile("v_cvt_pk_bf16_f32 %0, %1, %2" : "=v"(r) : "v"(lo), "v"(hi)); return r; }
; __device__ __forceinline__ float sigmoidf_(float v) { return __builtin_amdgcn_rcpf(1.f + __expf(-v)); }
;     __device__ __forceinline__ void operator()(const f32x4 (&acc)[2][2][4][2], const pg8::Unit& u, int wr, int wc, int fr, int fq, LAS unsigned char* sp) const {
;     ...
;                 const int row = row0 + ai * 128 + m * 16; const float s = rsl[ai * 128 + m * 16];
; #pragma unroll
;                 for (int bj = 0; bj < 2; ++bj) {
;                     f32x4 v0 = acc[ai][bj][m][0] * s, v1 = acc[ai][bj][m][1] * s;
;                     const int col = colt + bj * 128 + cw0;
;                     if (act == 2) { const f32x4 b0 = *(const LAS f32x4*)(bsl + bj * 128 + cw0), b1 = *(const LAS f32x4*)(bsl + bj * 128 + cw0 + 4);
;                         v0 += b0; v1 += b1;
; #pragma unroll
;                         for (int j = 0; j < 4; ++j) { v0[j] = sigmoidf_(v0[j]); v1[j] = sigmoidf_(v1[j]); } }
;                     else if (act == 1) {
; #pragma unroll
;                         for (int j = 0; j < 4; ++j) { v0[j] = v0[j] * sigmoidf_(v0[j]); v1[j] = v1[j] * sigmoidf_(v1[j]); } }
;                     u32x4 w; w.x = cvt_pk_bf16(v0[0], v0[1]); w.y = cvt_pk_bf16(v0[2], v0[3]); w.z = cvt_pk_bf16(v1[0], v1[1]); w.w = cvt_pk_bf16(v1[2], v1[3]);
;                     *(u32x4*)(dst + (size_t)row * pitch + col) = w;
.LBB0_310:
	v_cvt_pk_bf16_f32 v168, v163, v175
	v_cvt_pk_bf16_f32 v169, v177, v179
	v_cvt_pk_bf16_f32 v170, v174, v176
	v_cvt_pk_bf16_f32 v171, v178, v180
	ds_read_b32 v164, v203 offset:576
	global_store_dwordx4 v[166:167], v[168:171], off offset:256 nt
	s_cmp_gt_i32 s55, 1
	s_mov_b64 s[66:67], -1
	s_waitcnt lgkmcnt(0)
	v_pk_mul_f32 v[168:169], v[48:49], v[164:165] op_sel_hi:[1,0]
	v_pk_mul_f32 v[172:173], v[46:47], v[164:165] op_sel_hi:[1,0]
	v_pk_mul_f32 v[166:167], v[44:45], v[164:165] op_sel_hi:[1,0]
	v_pk_mul_f32 v[170:171], v[42:43], v[164:165] op_sel_hi:[1,0]
	s_cbranch_scc0 .LBB0_312
	ds_read_b128 v[174:177], v161 offset:1024
	ds_read_b128 v[178:181], v161 offset:1040
	s_mov_b64 s[66:67], 0
	s_waitcnt lgkmcnt(0)
	v_pk_add_f32 v[182:183], v[168:169], v[176:177]
	v_pk_add_f32 v[176:177], v[170:171], v[178:179]
	v_pk_add_f32 v[174:175], v[172:173], v[174:175]
	v_mul_f32_e32 v165, 0xbfb8aa3b, v176
	v_exp_f32_e32 v165, v165
	v_mul_f32_e32 v163, 0xbfb8aa3b, v174
	v_pk_add_f32 v[180:181], v[166:167], v[180:181]
	v_exp_f32_e32 v163, v163
	v_add_f32_e32 v165, 1.0, v165
	v_rcp_f32_e32 v174, v165
	v_mul_f32_e32 v165, 0xbfb8aa3b, v175
	v_exp_f32_e32 v165, v165
	v_add_f32_e32 v163, 1.0, v163
	v_rcp_f32_e32 v163, v163
	v_add_f32_e32 v165, 1.0, v165
	v_rcp_f32_e32 v175, v165
	v_mul_f32_e32 v165, 0xbfb8aa3b, v177
	v_exp_f32_e32 v165, v165
	s_nop 0
	v_add_f32_e32 v165, 1.0, v165
	v_rcp_f32_e32 v176, v165
	v_mul_f32_e32 v165, 0xbfb8aa3b, v182
	v_exp_f32_e32 v165, v165
	s_nop 0
	v_add_f32_e32 v165, 1.0, v165
	v_rcp_f32_e32 v177, v165
	v_mul_f32_e32 v165, 0xbfb8aa3b, v180
	v_exp_f32_e32 v165, v165
	s_nop 0
	v_add_f32_e32 v165, 1.0, v165
	v_rcp_f32_e32 v178, v165
	v_mul_f32_e32 v165, 0xbfb8aa3b, v183
	v_exp_f32_e32 v165, v165
	s_nop 0
	v_add_f32_e32 v165, 1.0, v165
	v_rcp_f32_e32 v179, v165
	v_mul_f32_e32 v165, 0xbfb8aa3b, v181
	v_exp_f32_e32 v165, v165
	s_nop 0
	v_add_f32_e32 v165, 1.0, v165
	v_rcp_f32_e32 v180, v165

; #define LAS __attribute__((address_space(3)))
; __device__ __forceinline__ unsigned cvt_pk_bf16(float lo, float hi) { unsigned r; asm volatile("v_cvt_pk_bf16_f32 %0, %1, %2" : "=v"(r) : "v"(lo), "v"(hi)); return r; }
; __device__ __forceinline__ float sigmoidf_(float v) { return __builtin_amdgcn_rcpf(1.f + __expf(-v)); }
;     __device__ __forceinline__ void operator()(const f32x4 (&acc)[2][2][4][2], const pg8::Unit& u, int wr, int wc, int fr, int fq, LAS unsigned char* sp) const {
;     ...
;                 const int row = row0 + ai * 128 + m * 16; const float s = rsl[ai * 128 + m * 16];
; #pragma unroll
;                 for (int bj = 0; bj < 2; ++bj) {
;                     f32x4 v0 = acc[ai][bj][m][0] * s, v1 = acc[ai][bj][m][1] * s;
;                     const int col = colt + bj * 128 + cw0;
;                     if (act == 2) { const f32x4 b0 = *(const LAS f32x4*)(bsl + bj * 128 + cw0), b1 = *(const LAS f32x4*)(bsl + bj * 128 + cw0 + 4);
;                         v0 += b0; v1 += b1;
; #pragma unroll
;                         for (int j = 0; j < 4; ++j) { v0[j] = sigmoidf_(v0[j]); v1[j] = sigmoidf_(v1[j]); } }
;                     else if (act == 1) {
; #pragma unroll
;                         for (int j = 0; j < 4; ++j) { v0[j] = v0[j] * sigmoidf_(v0[j]); v1[j] = v1[j] * sigmoidf_(v1[j]); } }
;                     u32x4 w; w.x = cvt_pk_bf16(v0[0], v0[1]); w.y = cvt_pk_bf16(v0[2], v0[3]); w.z = cvt_pk_bf16(v1[0], v1[1]); w.w = cvt_pk_bf16(v1[2], v1[3]);
;                     *(u32x4*)(dst + (size_t)row * pitch + col) = w;
.LBB0_316:
	v_add_u32_e32 v166, 0x90, v202
	v_ashrrev_i32_e32 v167, 31, v166
	v_mul_lo_u32 v168, s62, v167
	v_mul_lo_u32 v169, s63, v166
	v_mad_u64_u32 v[166:167], s[26:27], s62, v166, 0
	v_add3_u32 v167, v167, v168, v169
	v_lshl_add_u64 v[166:167], v[166:167], 1, s[64:65]
	v_cvt_pk_bf16_f32 v168, v163, v175
	v_cvt_pk_bf16_f32 v169, v177, v179
	v_cvt_pk_bf16_f32 v170, v174, v176
	v_cvt_pk_bf16_f32 v171, v178, v180
	v_lshl_add_u64 v[166:167], v[0:1], 1, v[166:167]
	global_store_dwordx4 v[166:167], v[168:171], off nt
	v_mov_b32_e32 v165, v164
	v_pk_mul_f32 v[172:173], v[38:39], v[164:165]
	v_mov_b32_e32 v170, v164
	v_mov_b32_e32 v171, v164
	v_pk_mul_f32 v[168:169], v[40:41], v[170:171]
	v_pk_mul_f32 v[170:171], v[36:37], v[170:171]
	v_pk_mul_f32 v[164:165], v[34:35], v[164:165]
	s_cmp_gt_i32 s55, 1
	s_mov_b64 s[66:67], -1
	s_cbranch_scc0 .LBB0_318
	ds_read_b128 v[174:177], v161 offset:1536
	ds_read_b128 v[178:181], v161 offset:1552
	s_mov_b64 s[66:67], 0
	s_waitcnt lgkmcnt(0)
	v_pk_add_f32 v[182:183], v[168:169], v[176:177]
	v_pk_add_f32 v[174:175], v[172:173], v[174:175]
	v_pk_add_f32 v[180:181], v[170:171], v[180:181]
	v_pk_add_f32 v[176:177], v[164:165], v[178:179]
	v_mul_f32_e32 v163, 0xbfb8aa3b, v174
	v_mul_f32_e32 v174, 0xbfb8aa3b, v176
	v_mul_f32_e32 v175, 0xbfb8aa3b, v175
	v_mul_f32_e32 v176, 0xbfb8aa3b, v177
	v_mul_f32_e32 v177, 0xbfb8aa3b, v182
	v_mul_f32_e32 v178, 0xbfb8aa3b, v180
	v_mul_f32_e32 v179, 0xbfb8aa3b, v183
	v_mul_f32_e32 v180, 0xbfb8aa3b, v181
	v_exp_f32_e32 v163, v163
	v_exp_f32_e32 v174, v174
	v_exp_f32_e32 v175, v175
	v_exp_f32_e32 v176, v176
	v_exp_f32_e32 v177, v177
	v_exp_f32_e32 v178, v178
	v_exp_f32_e32 v179, v179
	v_exp_f32_e32 v180, v180
	v_add_f32_e32 v163, 1.0, v163
	v_add_f32_e32 v174, 1.0, v174
	v_add_f32_e32 v175, 1.0, v175
	v_add_f32_e32 v176, 1.0, v176
	v_add_f32_e32 v177, 1.0, v177
	v_add_f32_e32 v178, 1.0, v178
	v_add_f32_e32 v179, 1.0, v179
	v_add_f32_e32 v180, 1.0, v180
	v_rcp_f32_e32 v163, v163
	v_rcp_f32_e32 v174, v174
	v_rcp_f32_e32 v175, v175
	v_rcp_f32_e32 v176, v176
	v_rcp_f32_e32 v177, v177
	v_rcp_f32_e32 v178, v178
	v_rcp_f32_e32 v179, v179
	v_rcp_f32_e32 v180, v180

; #define LAS __attribute__((address_space(3)))
; __device__ __forceinline__ unsigned cvt_pk_bf16(float lo, float hi) { unsigned r; asm volatile("v_cvt_pk_bf16_f32 %0, %1, %2" : "=v"(r) : "v"(lo), "v"(hi)); return r; }
; __device__ __forceinline__ float sigmoidf_(float v) { return __builtin_amdgcn_rcpf(1.f + __expf(-v)); }
;     __device__ __forceinline__ void operator()(const f32x4 (&acc)[2][2][4][2], const pg8::Unit& u, int wr, int wc, int fr, int fq, LAS unsigned char* sp) const {
;     ...
;                 const int row = row0 + ai * 128 + m * 16; const float s = rsl[ai * 128 + m * 16];
; #pragma unroll
;                 for (int bj = 0; bj < 2; ++bj) {
;                     f32x4 v0 = acc[ai][bj][m][0] * s, v1 = acc[ai][bj][m][1] * s;
;                     const int col = colt + bj * 128 + cw0;
;                     if (act == 2) { const f32x4 b0 = *(const LAS f32x4*)(bsl + bj * 128 + cw0), b1 = *(const LAS f32x4*)(bsl + bj * 128 + cw0 + 4);
;                         v0 += b0; v1 += b1;
; #pragma unroll
;                         for (int j = 0; j < 4; ++j) { v0[j] = sigmoidf_(v0[j]); v1[j] = sigmoidf_(v1[j]); } }
;                     else if (act == 1) {
; #pragma unroll
;                         for (int j = 0; j < 4; ++j) { v0[j] = v0[j] * sigmoidf_(v0[j]); v1[j] = v1[j] * sigmoidf_(v1[j]); } }
;                     u32x4 w; w.x = cvt_pk_bf16(v0[0], v0[1]); w.y = cvt_pk_bf16(v0[2], v0[3]); w.z = cvt_pk_bf16(v1[0], v1[1]); w.w = cvt_pk_bf16(v1[2], v1[3]);
;                     *(u32x4*)(dst + (size_t)row * pitch + col) = w;
.LBB0_322:
	v_cvt_pk_bf16_f32 v168, v163, v175
	v_cvt_pk_bf16_f32 v169, v177, v179
	v_cvt_pk_bf16_f32 v170, v174, v176
	v_cvt_pk_bf16_f32 v171, v178, v180
	ds_read_b32 v164, v203 offset:640
	global_store_dwordx4 v[166:167], v[168:171], off offset:256 nt
	s_cmp_gt_i32 s55, 1
	s_mov_b64 s[66:67], -1
	s_waitcnt lgkmcnt(0)
	v_pk_mul_f32 v[168:169], v[32:33], v[164:165] op_sel_hi:[1,0]
	v_pk_mul_f32 v[172:173], v[30:31], v[164:165] op_sel_hi:[1,0]
	v_pk_mul_f32 v[166:167], v[28:29], v[164:165] op_sel_hi:[1,0]
	v_pk_mul_f32 v[170:171], v[26:27], v[164:165] op_sel_hi:[1,0]
	s_cbranch_scc0 .LBB0_324
	ds_read_b128 v[174:177], v161 offset:1024
	ds_read_b128 v[178:181], v161 offset:1040
	s_mov_b64 s[66:67], 0
	s_waitcnt lgkmcnt(0)
	v_pk_add_f32 v[182:183], v[168:169], v[176:177]
	v_pk_add_f32 v[176:177], v[170:171], v[178:179]
	v_pk_add_f32 v[174:175], v[172:173], v[174:175]
	v_mul_f32_e32 v165, 0xbfb8aa3b, v176
	v_exp_f32_e32 v165, v165
	v_mul_f32_e32 v163, 0xbfb8aa3b, v174
	v_pk_add_f32 v[180:181], v[166:167], v[180:181]
	v_exp_f32_e32 v163, v163
	v_add_f32_e32 v165, 1.0, v165
	v_rcp_f32_e32 v174, v165
	v_mul_f32_e32 v165, 0xbfb8aa3b, v175
	v_exp_f32_e32 v165, v165
	v_add_f32_e32 v163, 1.0, v163
	v_rcp_f32_e32 v163, v163
	v_add_f32_e32 v165, 1.0, v165
	v_rcp_f32_e32 v175, v165
	v_mul_f32_e32 v165, 0xbfb8aa3b, v177
	v_exp_f32_e32 v165, v165
	s_nop 0
	v_add_f32_e32 v165, 1.0, v165
	v_rcp_f32_e32 v176, v165
	v_mul_f32_e32 v165, 0xbfb8aa3b, v182
	v_exp_f32_e32 v165, v165
	s_nop 0
	v_add_f32_e32 v165, 1.0, v165
	v_rcp_f32_e32 v177, v165
	v_mul_f32_e32 v165, 0xbfb8aa3b, v180
	v_exp_f32_e32 v165, v165
	s_nop 0
	v_add_f32_e32 v165, 1.0, v165
	v_rcp_f32_e32 v178, v165
	v_mul_f32_e32 v165, 0xbfb8aa3b, v183
	v_exp_f32_e32 v165, v165
	s_nop 0
	v_add_f32_e32 v165, 1.0, v165
	v_rcp_f32_e32 v179, v165
	v_mul_f32_e32 v165, 0xbfb8aa3b, v181
	v_exp_f32_e32 v165, v165
	s_nop 0
	v_add_f32_e32 v165, 1.0, v165
	v_rcp_f32_e32 v180, v165

; #define LAS __attribute__((address_space(3)))
; __device__ __forceinline__ unsigned cvt_pk_bf16(float lo, float hi) { unsigned r; asm volatile("v_cvt_pk_bf16_f32 %0, %1, %2" : "=v"(r) : "v"(lo), "v"(hi)); return r; }
; __device__ __forceinline__ float sigmoidf_(float v) { return __builtin_amdgcn_rcpf(1.f + __expf(-v)); }
;     __device__ __forceinline__ void operator()(const f32x4 (&acc)[2][2][4][2], const pg8::Unit& u, int wr, int wc, int fr, int fq, LAS unsigned char* sp) const {
;     ...
;                 const int row = row0 + ai * 128 + m * 16; const float s = rsl[ai * 128 + m * 16];
; #pragma unroll
;                 for (int bj = 0; bj < 2; ++bj) {
;                     f32x4 v0 = acc[ai][bj][m][0] * s, v1 = acc[ai][bj][m][1] * s;
;                     const int col = colt + bj * 128 + cw0;
;                     if (act == 2) { const f32x4 b0 = *(const LAS f32x4*)(bsl + bj * 128 + cw0), b1 = *(const LAS f32x4*)(bsl + bj * 128 + cw0 + 4);
;                         v0 += b0; v1 += b1;
; #pragma unroll
;                         for (int j = 0; j < 4; ++j) { v0[j] = sigmoidf_(v0[j]); v1[j] = sigmoidf_(v1[j]); } }
;                     else if (act == 1) {
; #pragma unroll
;                         for (int j = 0; j < 4; ++j) { v0[j] = v0[j] * sigmoidf_(v0[j]); v1[j] = v1[j] * sigmoidf_(v1[j]); } }
;                     u32x4 w; w.x = cvt_pk_bf16(v0[0], v0[1]); w.y = cvt_pk_bf16(v0[2], v0[3]); w.z = cvt_pk_bf16(v1[0], v1[1]); w.w = cvt_pk_bf16(v1[2], v1[3]);
;                     *(u32x4*)(dst + (size_t)row * pitch + col) = w;
.LBB0_328:
	v_add_u32_e32 v166, 0xa0, v202
	v_ashrrev_i32_e32 v167, 31, v166
	v_mul_lo_u32 v168, s62, v167
	v_mul_lo_u32 v169, s63, v166
	v_mad_u64_u32 v[166:167], s[26:27], s62, v166, 0
	v_add3_u32 v167, v167, v168, v169
	v_lshl_add_u64 v[166:167], v[166:167], 1, s[64:65]
	v_cvt_pk_bf16_f32 v168, v163, v175
	v_cvt_pk_bf16_f32 v169, v177, v179
	v_cvt_pk_bf16_f32 v170, v174, v176
	v_cvt_pk_bf16_f32 v171, v178, v180
	v_lshl_add_u64 v[166:167], v[0:1], 1, v[166:167]
	global_store_dwordx4 v[166:167], v[168:171], off nt
	v_mov_b32_e32 v165, v164
	v_pk_mul_f32 v[172:173], v[22:23], v[164:165]
	v_mov_b32_e32 v170, v164
	v_mov_b32_e32 v171, v164
	v_pk_mul_f32 v[168:169], v[24:25], v[170:171]
	v_pk_mul_f32 v[170:171], v[20:21], v[170:171]
	v_pk_mul_f32 v[164:165], v[18:19], v[164:165]
	s_cmp_gt_i32 s55, 1
	s_mov_b64 s[66:67], -1
	s_cbranch_scc0 .LBB0_330
	ds_read_b128 v[174:177], v161 offset:1536
	ds_read_b128 v[178:181], v161 offset:1552
	s_mov_b64 s[66:67], 0
	s_waitcnt lgkmcnt(0)
	v_pk_add_f32 v[182:183], v[168:169], v[176:177]
	v_pk_add_f32 v[174:175], v[172:173], v[174:175]
	v_pk_add_f32 v[180:181], v[170:171], v[180:181]
	v_pk_add_f32 v[176:177], v[164:165], v[178:179]
	v_mul_f32_e32 v163, 0xbfb8aa3b, v174
	v_mul_f32_e32 v174, 0xbfb8aa3b, v176
	v_mul_f32_e32 v175, 0xbfb8aa3b, v175
	v_mul_f32_e32 v176, 0xbfb8aa3b, v177
	v_mul_f32_e32 v177, 0xbfb8aa3b, v182
	v_mul_f32_e32 v178, 0xbfb8aa3b, v180
	v_mul_f32_e32 v179, 0xbfb8aa3b, v183
	v_mul_f32_e32 v180, 0xbfb8aa3b, v181
	v_exp_f32_e32 v163, v163
	v_exp_f32_e32 v174, v174
	v_exp_f32_e32 v175, v175
	v_exp_f32_e32 v176, v176
	v_exp_f32_e32 v177, v177
	v_exp_f32_e32 v178, v178
	v_exp_f32_e32 v179, v179
	v_exp_f32_e32 v180, v180
	v_add_f32_e32 v163, 1.0, v163
	v_add_f32_e32 v174, 1.0, v174
	v_add_f32_e32 v175, 1.0, v175
	v_add_f32_e32 v176, 1.0, v176
	v_add_f32_e32 v177, 1.0, v177
	v_add_f32_e32 v178, 1.0, v178
	v_add_f32_e32 v179, 1.0, v179
	v_add_f32_e32 v180, 1.0, v180
	v_rcp_f32_e32 v163, v163
	v_rcp_f32_e32 v174, v174
	v_rcp_f32_e32 v175, v175
	v_rcp_f32_e32 v176, v176
	v_rcp_f32_e32 v177, v177
	v_rcp_f32_e32 v178, v178
	v_rcp_f32_e32 v179, v179
	v_rcp_f32_e32 v180, v180

; #define LAS __attribute__((address_space(3)))
; __device__ __forceinline__ unsigned cvt_pk_bf16(float lo, float hi) { unsigned r; asm volatile("v_cvt_pk_bf16_f32 %0, %1, %2" : "=v"(r) : "v"(lo), "v"(hi)); return r; }
; __device__ __forceinline__ float sigmoidf_(float v) { return __builtin_amdgcn_rcpf(1.f + __expf(-v)); }
;     __device__ __forceinline__ void operator()(const f32x4 (&acc)[2][2][4][2], const pg8::Unit& u, int wr, int wc, int fr, int fq, LAS unsigned char* sp) const {
;     ...
;                 const int row = row0 + ai * 128 + m * 16; const float s = rsl[ai * 128 + m * 16];
; #pragma unroll
;                 for (int bj = 0; bj < 2; ++bj) {
;                     f32x4 v0 = acc[ai][bj][m][0] * s, v1 = acc[ai][bj][m][1] * s;
;                     const int col = colt + bj * 128 + cw0;
;                     if (act == 2) { const f32x4 b0 = *(const LAS f32x4*)(bsl + bj * 128 + cw0), b1 = *(const LAS f32x4*)(bsl + bj * 128 + cw0 + 4);
;                         v0 += b0; v1 += b1;
; #pragma unroll
;                         for (int j = 0; j < 4; ++j) { v0[j] = sigmoidf_(v0[j]); v1[j] = sigmoidf_(v1[j]); } }
;                     else if (act == 1) {
; #pragma unroll
;                         for (int j = 0; j < 4; ++j) { v0[j] = v0[j] * sigmoidf_(v0[j]); v1[j] = v1[j] * sigmoidf_(v1[j]); } }
;                     u32x4 w; w.x = cvt_pk_bf16(v0[0], v0[1]); w.y = cvt_pk_bf16(v0[2], v0[3]); w.z = cvt_pk_bf16(v1[0], v1[1]); w.w = cvt_pk_bf16(v1[2], v1[3]);
;                     *(u32x4*)(dst + (size_t)row * pitch + col) = w;
.LBB0_334:
	v_cvt_pk_bf16_f32 v168, v163, v175
	v_cvt_pk_bf16_f32 v169, v177, v179
	v_cvt_pk_bf16_f32 v170, v174, v176
	v_cvt_pk_bf16_f32 v171, v178, v180
	ds_read_b32 v164, v203 offset:704
	global_store_dwordx4 v[166:167], v[168:171], off offset:256 nt
	s_cmp_gt_i32 s55, 1
	s_mov_b64 s[66:67], -1
	s_waitcnt lgkmcnt(0)
	v_pk_mul_f32 v[168:169], v[16:17], v[164:165] op_sel_hi:[1,0]
	v_pk_mul_f32 v[172:173], v[14:15], v[164:165] op_sel_hi:[1,0]
	v_pk_mul_f32 v[166:167], v[12:13], v[164:165] op_sel_hi:[1,0]
	v_pk_mul_f32 v[170:171], v[10:11], v[164:165] op_sel_hi:[1,0]
	s_cbranch_scc0 .LBB0_336
	ds_read_b128 v[174:177], v161 offset:1024
	ds_read_b128 v[178:181], v161 offset:1040
	s_mov_b64 s[66:67], 0
	s_waitcnt lgkmcnt(0)
	v_pk_add_f32 v[182:183], v[168:169], v[176:177]
	v_pk_add_f32 v[176:177], v[170:171], v[178:179]
	v_pk_add_f32 v[174:175], v[172:173], v[174:175]
	v_mul_f32_e32 v165, 0xbfb8aa3b, v176
	v_exp_f32_e32 v165, v165
	v_mul_f32_e32 v163, 0xbfb8aa3b, v174
	v_pk_add_f32 v[180:181], v[166:167], v[180:181]
	v_exp_f32_e32 v163, v163
	v_add_f32_e32 v165, 1.0, v165
	v_rcp_f32_e32 v174, v165
	v_mul_f32_e32 v165, 0xbfb8aa3b, v175
	v_exp_f32_e32 v165, v165
	v_add_f32_e32 v163, 1.0, v163
	v_rcp_f32_e32 v163, v163
	v_add_f32_e32 v165, 1.0, v165
	v_rcp_f32_e32 v175, v165
	v_mul_f32_e32 v165, 0xbfb8aa3b, v177
	v_exp_f32_e32 v165, v165
	s_nop 0
	v_add_f32_e32 v165, 1.0, v165
	v_rcp_f32_e32 v176, v165
	v_mul_f32_e32 v165, 0xbfb8aa3b, v182
	v_exp_f32_e32 v165, v165
	s_nop 0
	v_add_f32_e32 v165, 1.0, v165
	v_rcp_f32_e32 v177, v165
	v_mul_f32_e32 v165, 0xbfb8aa3b, v180
	v_exp_f32_e32 v165, v165
	s_nop 0
	v_add_f32_e32 v165, 1.0, v165
	v_rcp_f32_e32 v178, v165
	v_mul_f32_e32 v165, 0xbfb8aa3b, v183
	v_exp_f32_e32 v165, v165
	s_nop 0
	v_add_f32_e32 v165, 1.0, v165
	v_rcp_f32_e32 v179, v165
	v_mul_f32_e32 v165, 0xbfb8aa3b, v181
	v_exp_f32_e32 v165, v165
	s_nop 0
	v_add_f32_e32 v165, 1.0, v165
	v_rcp_f32_e32 v180, v165

; #define LAS __attribute__((address_space(3)))
; __device__ __forceinline__ unsigned cvt_pk_bf16(float lo, float hi) { unsigned r; asm volatile("v_cvt_pk_bf16_f32 %0, %1, %2" : "=v"(r) : "v"(lo), "v"(hi)); return r; }
; __device__ __forceinline__ float sigmoidf_(float v) { return __builtin_amdgcn_rcpf(1.f + __expf(-v)); }
;     __device__ __forceinline__ void operator()(const f32x4 (&acc)[2][2][4][2], const pg8::Unit& u, int wr, int wc, int fr, int fq, LAS unsigned char* sp) const {
;     ...
;                 const int row = row0 + ai * 128 + m * 16; const float s = rsl[ai * 128 + m * 16];
; #pragma unroll
;                 for (int bj = 0; bj < 2; ++bj) {
;                     f32x4 v0 = acc[ai][bj][m][0] * s, v1 = acc[ai][bj][m][1] * s;
;                     const int col = colt + bj * 128 + cw0;
;                     if (act == 2) { const f32x4 b0 = *(const LAS f32x4*)(bsl + bj * 128 + cw0), b1 = *(const LAS f32x4*)(bsl + bj * 128 + cw0 + 4);
;                         v0 += b0; v1 += b1;
; #pragma unroll
;                         for (int j = 0; j < 4; ++j) { v0[j] = sigmoidf_(v0[j]); v1[j] = sigmoidf_(v1[j]); } }
;                     else if (act == 1) {
; #pragma unroll
;                         for (int j = 0; j < 4; ++j) { v0[j] = v0[j] * sigmoidf_(v0[j]); v1[j] = v1[j] * sigmoidf_(v1[j]); } }
;                     u32x4 w; w.x = cvt_pk_bf16(v0[0], v0[1]); w.y = cvt_pk_bf16(v0[2], v0[3]); w.z = cvt_pk_bf16(v1[0], v1[1]); w.w = cvt_pk_bf16(v1[2], v1[3]);
;                     *(u32x4*)(dst + (size_t)row * pitch + col) = w;
.LBB0_340:
	v_add_u32_e32 v166, 0xb0, v202
	v_ashrrev_i32_e32 v167, 31, v166
	v_mul_lo_u32 v168, s62, v167
	v_mul_lo_u32 v169, s63, v166
	v_mad_u64_u32 v[166:167], s[26:27], s62, v166, 0
	v_add3_u32 v167, v167, v168, v169
	v_lshl_add_u64 v[166:167], v[166:167], 1, s[64:65]
	v_cvt_pk_bf16_f32 v168, v163, v175
	v_cvt_pk_bf16_f32 v169, v177, v179
	v_cvt_pk_bf16_f32 v170, v174, v176
	v_cvt_pk_bf16_f32 v171, v178, v180
	v_lshl_add_u64 v[166:167], v[0:1], 1, v[166:167]
	global_store_dwordx4 v[166:167], v[168:171], off nt
	v_mov_b32_e32 v165, v164
	v_pk_mul_f32 v[172:173], v[6:7], v[164:165]
	v_mov_b32_e32 v170, v164
	v_mov_b32_e32 v171, v164
	v_pk_mul_f32 v[168:169], v[8:9], v[170:171]
	v_pk_mul_f32 v[170:171], v[4:5], v[170:171]
	v_pk_mul_f32 v[164:165], v[2:3], v[164:165]
	s_cmp_gt_i32 s55, 1
	s_mov_b64 s[66:67], -1
	s_cbranch_scc0 .LBB0_342
	ds_read_b128 v[174:177], v161 offset:1536
	ds_read_b128 v[178:181], v161 offset:1552
	s_mov_b64 s[66:67], 0
	s_waitcnt lgkmcnt(0)
	v_pk_add_f32 v[182:183], v[168:169], v[176:177]
	v_pk_add_f32 v[176:177], v[164:165], v[178:179]
	v_pk_add_f32 v[174:175], v[172:173], v[174:175]
	v_mul_f32_e32 v161, 0xbfb8aa3b, v176
	v_exp_f32_e32 v161, v161
	v_mul_f32_e32 v0, 0xbfb8aa3b, v174
	v_pk_add_f32 v[180:181], v[170:171], v[180:181]
	v_exp_f32_e32 v0, v0
	v_add_f32_e32 v161, 1.0, v161
	v_rcp_f32_e32 v163, v161
	v_mul_f32_e32 v161, 0xbfb8aa3b, v175
	v_exp_f32_e32 v161, v161
	v_add_f32_e32 v0, 1.0, v0
	v_rcp_f32_e32 v0, v0
	v_add_f32_e32 v161, 1.0, v161
	v_rcp_f32_e32 v174, v161
	v_mul_f32_e32 v161, 0xbfb8aa3b, v177
	v_exp_f32_e32 v161, v161
	s_nop 0
	v_add_f32_e32 v161, 1.0, v161
	v_rcp_f32_e32 v175, v161
	v_mul_f32_e32 v161, 0xbfb8aa3b, v182
	v_exp_f32_e32 v161, v161
	s_nop 0
	v_add_f32_e32 v161, 1.0, v161
	v_rcp_f32_e32 v176, v161
	v_mul_f32_e32 v161, 0xbfb8aa3b, v180
	v_exp_f32_e32 v161, v161
	s_nop 0
	v_add_f32_e32 v161, 1.0, v161
	v_rcp_f32_e32 v177, v161
	v_mul_f32_e32 v161, 0xbfb8aa3b, v183
	v_exp_f32_e32 v161, v161
	s_nop 0
	v_add_f32_e32 v161, 1.0, v161
	v_rcp_f32_e32 v178, v161
	v_mul_f32_e32 v161, 0xbfb8aa3b, v181
	v_exp_f32_e32 v161, v161
	s_nop 0
	v_add_f32_e32 v161, 1.0, v161
	v_rcp_f32_e32 v179, v161

; __device__ __forceinline__ unsigned cvt_pk_bf16(float lo, float hi) { unsigned r; asm volatile("v_cvt_pk_bf16_f32 %0, %1, %2" : "=v"(r) : "v"(lo), "v"(hi)); return r; }
;     __device__ __forceinline__ void operator()(const f32x4 (&acc)[2][2][4][2], const pg8::Unit& u, int wr, int wc, int fr, int fq, LAS unsigned char* sp) const {
;     ...
;                     u32x4 w; w.x = cvt_pk_bf16(v0[0], v0[1]); w.y = cvt_pk_bf16(v0[2], v0[3]); w.z = cvt_pk_bf16(v1[0], v1[1]); w.w = cvt_pk_bf16(v1[2], v1[3]);
;                     *(u32x4*)(dst + (size_t)row * pitch + col) = w;
.LBB0_346:
	v_cvt_pk_bf16_f32 v168, v0, v174
	v_cvt_pk_bf16_f32 v169, v176, v178
	v_cvt_pk_bf16_f32 v170, v163, v175
	v_cvt_pk_bf16_f32 v171, v177, v179
	global_store_dwordx4 v[166:167], v[168:171], off offset:256 nt

; __device__ __forceinline__ unsigned cvt_pk_bf16(float lo, float hi) { unsigned r; asm volatile("v_cvt_pk_bf16_f32 %0, %1, %2" : "=v"(r) : "v"(lo), "v"(hi)); return r; }
;     __device__ __forceinline__ void operator()(const f32x4 (&acc)[2][2][4][2], const pg8::Unit& u, int wr, int wc, int fr, int fq, LAS unsigned char* sp) const {
;     ...
;                     const int row = row0 + ai * 128 + m * 16; const float s = rsl[ai * 128 + m * 16];
;                     f32x4 v[2][2];
; #pragma unroll
;                     for (int bj = 0; bj < 2; ++bj)
; #pragma unroll
;                         for (int n = 0; n < 2; ++n) v[bj][n] = acc[ai][bj][m][n] * s;
;                     if (act == 3) {
;                         float q = 0.f;
; #pragma unroll
;                         for (int bj = 0; bj < 2; ++bj)
; #pragma unroll
;                             for (int n = 0; n < 2; ++n) q += (v[bj][n][0] * v[bj][n][0] + v[bj][n][1] * v[bj][n][1]) + (v[bj][n][2] * v[bj][n][2] + v[bj][n][3] * v[bj][n][3]);
;                         q += __shfl_xor(q, 16); q += __shfl_xor(q, 32);
;                         const float ri = rsqrtf(q * (1.f / 64.f) + EPS) * osc;
; #pragma unroll
;                         for (int bj = 0; bj < 2; ++bj)
; #pragma unroll
;                             for (int n = 0; n < 2; ++n) { const f32x4 g = *(const f32x4*)(gn + 32 * bj + 8 * fq + 4 * n); v[bj][n] = v[bj][n] * g * ri; }
;                     } else {
;                         const int pos = row & (SEQ - 1);
; #pragma unroll
;                         for (int n = 0; n < 2; ++n) { const f32x4 cs = *(const f32x4*)(rot + pos * 32 + 8 * fq + 4 * n), sn = *(const f32x4*)(rot + 4096 * 32 + pos * 32 + 8 * fq + 4 * n);
;                             const f32x4 x1 = v[0][n], x2 = v[1][n]; v[0][n] = (x1 * cs - x2 * sn) * osc; v[1][n] = (x2 * cs + x1 * sn) * osc; }
;                     }
; #pragma unroll
;                     for (int bj = 0; bj < 2; ++bj) { u32x4 w; w.x = cvt_pk_bf16(v[bj][0][0], v[bj][0][1]); w.y = cvt_pk_bf16(v[bj][0][2], v[bj][0][3]); w.z = cvt_pk_bf16(v[bj][1][0], v[bj][1][1]); w.w = cvt_pk_bf16(v[bj][1][2], v[bj][1][3]);
;                         *(u32x4*)(dst + (size_t)row * pitch + colt + cwh + 32 * bj) = w; }
.LBB0_353:
	s_lshl_b64 s[8:9], s[28:29], 1
	s_add_u32 s8, s64, s8
	s_addc_u32 s9, s65, s9
	v_mov_b32_e32 v163, v1
	v_ashrrev_i32_e32 v0, 31, v202
	v_lshl_add_u64 v[168:169], s[8:9], 0, v[162:163]
	v_mul_lo_u32 v161, s63, v202
	v_mul_lo_u32 v0, s62, v0
	v_mad_u64_u32 v[170:171], s[8:9], s62, v202, 0
	v_add3_u32 v171, v171, v0, v161
	v_lshl_add_u64 v[170:171], v[170:171], 1, v[168:169]
	v_cvt_pk_bf16_f32 v114, v114, v115
	v_cvt_pk_bf16_f32 v115, v116, v117
	v_cvt_pk_bf16_f32 v116, v118, v119
	v_cvt_pk_bf16_f32 v117, v120, v121
	global_store_dwordx4 v[170:171], v[114:117], off nt
	v_or_b32_e32 v161, 16, v202
	s_andn2_b64 vcc, exec, s[66:67]
	v_cvt_pk_bf16_f32 v114, v126, v127
	v_cvt_pk_bf16_f32 v115, v128, v129
	v_cvt_pk_bf16_f32 v116, v122, v123
	v_cvt_pk_bf16_f32 v117, v124, v125
	ds_read_b32 v0, v203 offset:64
	global_store_dwordx4 v[170:171], v[114:117], off offset:64 nt
	s_mov_b64 s[64:65], -1
	s_waitcnt lgkmcnt(0)
	v_pk_mul_f32 v[122:123], v[112:113], v[0:1] op_sel_hi:[1,0]
	v_pk_mul_f32 v[124:125], v[110:111], v[0:1] op_sel_hi:[1,0]
	v_pk_mul_f32 v[126:127], v[108:109], v[0:1] op_sel_hi:[1,0]
	v_pk_mul_f32 v[128:129], v[106:107], v[0:1] op_sel_hi:[1,0]
	v_pk_mul_f32 v[118:119], v[104:105], v[0:1] op_sel_hi:[1,0]
	v_pk_mul_f32 v[120:121], v[102:103], v[0:1] op_sel_hi:[1,0]
	v_pk_mul_f32 v[114:115], v[100:101], v[0:1] op_sel_hi:[1,0]
	v_pk_mul_f32 v[116:117], v[98:99], v[0:1] op_sel_hi:[1,0]
	v_cndmask_b32_e64 v0, 0, 1, s[66:67]
	v_cmp_ne_u32_e64 s[8:9], 1, v0
	s_cbranch_vccnz .LBB0_355
	v_lshlrev_b32_e32 v0, 7, v161
	v_and_b32_e32 v0, 0x7ef80, v0
	v_lshl_add_u64 v[98:99], v[142:143], 0, v[0:1]
	v_lshl_add_u64 v[100:101], v[144:145], 0, v[0:1]
	global_load_dwordx4 v[106:109], v[98:99], off offset:16
	global_load_dwordx4 v[102:105], v[98:99], off
	global_load_dwordx4 v[170:173], v[100:101], off offset:16
	global_load_dwordx4 v[110:113], v[100:101], off
	v_mov_b32_e32 v176, v164
	v_mov_b32_e32 v177, v164
	s_mov_b64 s[64:65], 0
	s_waitcnt vmcnt(0)
	v_pk_mul_f32 v[98:99], v[118:119], v[112:113]
	v_pk_mul_f32 v[100:101], v[120:121], v[110:111]
	v_pk_mul_f32 v[112:113], v[122:123], v[112:113]
	v_pk_mul_f32 v[110:111], v[124:125], v[110:111]
	v_pk_fma_f32 v[98:99], v[122:123], v[104:105], v[98:99] neg_lo:[0,0,1] neg_hi:[0,0,1]
	v_pk_fma_f32 v[174:175], v[124:125], v[102:103], v[100:101] neg_lo:[0,0,1] neg_hi:[0,0,1]
	v_pk_fma_f32 v[104:105], v[118:119], v[104:105], v[112:113]
	v_pk_fma_f32 v[102:103], v[120:121], v[102:103], v[110:111]
	v_pk_mul_f32 v[112:113], v[176:177], v[104:105]
	v_pk_mul_f32 v[110:111], v[164:165], v[102:103]
	v_pk_mul_f32 v[102:103], v[114:115], v[172:173]
	v_pk_mul_f32 v[104:105], v[116:117], v[170:171]
	v_pk_mul_f32 v[172:173], v[126:127], v[172:173]
	v_pk_mul_f32 v[170:171], v[128:129], v[170:171]
	v_pk_mul_f32 v[100:101], v[176:177], v[98:99]
	v_pk_mul_f32 v[98:99], v[164:165], v[174:175]
	v_pk_fma_f32 v[102:103], v[126:127], v[108:109], v[102:103] neg_lo:[0,0,1] neg_hi:[0,0,1]
	v_pk_fma_f32 v[174:175], v[128:129], v[106:107], v[104:105] neg_lo:[0,0,1] neg_hi:[0,0,1]
	v_pk_fma_f32 v[108:109], v[114:115], v[108:109], v[172:173]
	v_pk_fma_f32 v[106:107], v[116:117], v[106:107], v[170:171]
	v_pk_mul_f32 v[104:105], v[176:177], v[102:103]
	v_pk_mul_f32 v[102:103], v[164:165], v[174:175]
	v_pk_mul_f32 v[108:109], v[176:177], v[108:109]
	v_pk_mul_f32 v[106:107], v[164:165], v[106:107]

; __device__ __forceinline__ unsigned cvt_pk_bf16(float lo, float hi) { unsigned r; asm volatile("v_cvt_pk_bf16_f32 %0, %1, %2" : "=v"(r) : "v"(lo), "v"(hi)); return r; }
;     __device__ __forceinline__ void operator()(const f32x4 (&acc)[2][2][4][2], const pg8::Unit& u, int wr, int wc, int fr, int fq, LAS unsigned char* sp) const {
;     ...
;                     const int row = row0 + ai * 128 + m * 16; const float s = rsl[ai * 128 + m * 16];
;                     f32x4 v[2][2];
; #pragma unroll
;                     for (int bj = 0; bj < 2; ++bj)
; #pragma unroll
;                         for (int n = 0; n < 2; ++n) v[bj][n] = acc[ai][bj][m][n] * s;
;                     if (act == 3) {
;                         float q = 0.f;
; #pragma unroll
;                         for (int bj = 0; bj < 2; ++bj)
; #pragma unroll
;                             for (int n = 0; n < 2; ++n) q += (v[bj][n][0] * v[bj][n][0] + v[bj][n][1] * v[bj][n][1]) + (v[bj][n][2] * v[bj][n][2] + v[bj][n][3] * v[bj][n][3]);
;                         q += __shfl_xor(q, 16); q += __shfl_xor(q, 32);
;                         const float ri = rsqrtf(q * (1.f / 64.f) + EPS) * osc;
; #pragma unroll
;                         for (int bj = 0; bj < 2; ++bj)
; #pragma unroll
;                             for (int n = 0; n < 2; ++n) { const f32x4 g = *(const f32x4*)(gn + 32 * bj + 8 * fq + 4 * n); v[bj][n] = v[bj][n] * g * ri; }
;                     } else {
;                         const int pos = row & (SEQ - 1);
; #pragma unroll
;                         for (int n = 0; n < 2; ++n) { const f32x4 cs = *(const f32x4*)(rot + pos * 32 + 8 * fq + 4 * n), sn = *(const f32x4*)(rot + 4096 * 32 + pos * 32 + 8 * fq + 4 * n);
;                             const f32x4 x1 = v[0][n], x2 = v[1][n]; v[0][n] = (x1 * cs - x2 * sn) * osc; v[1][n] = (x2 * cs + x1 * sn) * osc; }
;                     }
; #pragma unroll
;                     for (int bj = 0; bj < 2; ++bj) { u32x4 w; w.x = cvt_pk_bf16(v[bj][0][0], v[bj][0][1]); w.y = cvt_pk_bf16(v[bj][0][2], v[bj][0][3]); w.z = cvt_pk_bf16(v[bj][1][0], v[bj][1][1]); w.w = cvt_pk_bf16(v[bj][1][2], v[bj][1][3]);
;                         *(u32x4*)(dst + (size_t)row * pitch + colt + cwh + 32 * bj) = w; }
.LBB0_357:
	v_ashrrev_i32_e32 v0, 31, v161
	v_mul_lo_u32 v116, s63, v161
	v_mul_lo_u32 v0, s62, v0
	v_mad_u64_u32 v[114:115], s[26:27], s62, v161, 0
	v_add3_u32 v115, v115, v0, v116
	v_lshl_add_u64 v[114:115], v[114:115], 1, v[168:169]
	v_cvt_pk_bf16_f32 v98, v98, v99
	v_cvt_pk_bf16_f32 v99, v100, v101
	v_cvt_pk_bf16_f32 v100, v102, v103
	v_cvt_pk_bf16_f32 v101, v104, v105
	global_store_dwordx4 v[114:115], v[98:101], off nt
	s_and_b64 vcc, exec, s[8:9]
	s_mov_b64 s[64:65], -1
	v_cvt_pk_bf16_f32 v98, v110, v111
	v_cvt_pk_bf16_f32 v99, v112, v113
	v_cvt_pk_bf16_f32 v100, v106, v107
	v_cvt_pk_bf16_f32 v101, v108, v109
	ds_read_b32 v0, v203 offset:128
	global_store_dwordx4 v[114:115], v[98:101], off offset:64 nt
	v_or_b32_e32 v114, 32, v202
	s_waitcnt lgkmcnt(0)
	v_pk_mul_f32 v[106:107], v[96:97], v[0:1] op_sel_hi:[1,0]
	v_pk_mul_f32 v[108:109], v[94:95], v[0:1] op_sel_hi:[1,0]
	v_pk_mul_f32 v[110:111], v[92:93], v[0:1] op_sel_hi:[1,0]
	v_pk_mul_f32 v[112:113], v[90:91], v[0:1] op_sel_hi:[1,0]
	v_pk_mul_f32 v[102:103], v[88:89], v[0:1] op_sel_hi:[1,0]
	v_pk_mul_f32 v[104:105], v[86:87], v[0:1] op_sel_hi:[1,0]
	v_pk_mul_f32 v[98:99], v[84:85], v[0:1] op_sel_hi:[1,0]
	v_pk_mul_f32 v[100:101], v[82:83], v[0:1] op_sel_hi:[1,0]
	s_cbranch_vccnz .LBB0_359
	v_lshlrev_b32_e32 v0, 7, v114
	v_and_b32_e32 v0, 0x7f780, v0
	v_lshl_add_u64 v[82:83], v[142:143], 0, v[0:1]
	v_lshl_add_u64 v[84:85], v[144:145], 0, v[0:1]
	global_load_dwordx4 v[90:93], v[82:83], off offset:16
	global_load_dwordx4 v[86:89], v[82:83], off
	global_load_dwordx4 v[116:119], v[84:85], off offset:16
	global_load_dwordx4 v[94:97], v[84:85], off
	v_mov_b32_e32 v122, v164
	v_mov_b32_e32 v123, v164
	s_mov_b64 s[64:65], 0
	s_waitcnt vmcnt(0)
	v_pk_mul_f32 v[82:83], v[102:103], v[96:97]
	v_pk_mul_f32 v[84:85], v[104:105], v[94:95]
	v_pk_mul_f32 v[96:97], v[106:107], v[96:97]
	v_pk_mul_f32 v[94:95], v[108:109], v[94:95]
	v_pk_fma_f32 v[82:83], v[106:107], v[88:89], v[82:83] neg_lo:[0,0,1] neg_hi:[0,0,1]
	v_pk_fma_f32 v[120:121], v[108:109], v[86:87], v[84:85] neg_lo:[0,0,1] neg_hi:[0,0,1]
	v_pk_fma_f32 v[88:89], v[102:103], v[88:89], v[96:97]
	v_pk_fma_f32 v[86:87], v[104:105], v[86:87], v[94:95]
	v_pk_mul_f32 v[96:97], v[122:123], v[88:89]
	v_pk_mul_f32 v[94:95], v[164:165], v[86:87]
	v_pk_mul_f32 v[86:87], v[98:99], v[118:119]
	v_pk_mul_f32 v[88:89], v[100:101], v[116:117]
	v_pk_mul_f32 v[118:119], v[110:111], v[118:119]
	v_pk_mul_f32 v[116:117], v[112:113], v[116:117]
	v_pk_mul_f32 v[84:85], v[122:123], v[82:83]
	v_pk_mul_f32 v[82:83], v[164:165], v[120:121]
	v_pk_fma_f32 v[86:87], v[110:111], v[92:93], v[86:87] neg_lo:[0,0,1] neg_hi:[0,0,1]
	v_pk_fma_f32 v[120:121], v[112:113], v[90:91], v[88:89] neg_lo:[0,0,1] neg_hi:[0,0,1]
	v_pk_fma_f32 v[92:93], v[98:99], v[92:93], v[118:119]
	v_pk_fma_f32 v[90:91], v[100:101], v[90:91], v[116:117]
	v_pk_mul_f32 v[88:89], v[122:123], v[86:87]
	v_pk_mul_f32 v[86:87], v[164:165], v[120:121]
	v_pk_mul_f32 v[92:93], v[122:123], v[92:93]
	v_pk_mul_f32 v[90:91], v[164:165], v[90:91]

; __device__ __forceinline__ unsigned cvt_pk_bf16(float lo, float hi) { unsigned r; asm volatile("v_cvt_pk_bf16_f32 %0, %1, %2" : "=v"(r) : "v"(lo), "v"(hi)); return r; }
;     __device__ __forceinline__ void operator()(const f32x4 (&acc)[2][2][4][2], const pg8::Unit& u, int wr, int wc, int fr, int fq, LAS unsigned char* sp) const {
;     ...
;                     const int row = row0 + ai * 128 + m * 16; const float s = rsl[ai * 128 + m * 16];
;                     f32x4 v[2][2];
; #pragma unroll
;                     for (int bj = 0; bj < 2; ++bj)
; #pragma unroll
;                         for (int n = 0; n < 2; ++n) v[bj][n] = acc[ai][bj][m][n] * s;
;                     if (act == 3) {
;                         float q = 0.f;
; #pragma unroll
;                         for (int bj = 0; bj < 2; ++bj)
; #pragma unroll
;                             for (int n = 0; n < 2; ++n) q += (v[bj][n][0] * v[bj][n][0] + v[bj][n][1] * v[bj][n][1]) + (v[bj][n][2] * v[bj][n][2] + v[bj][n][3] * v[bj][n][3]);
;                         q += __shfl_xor(q, 16); q += __shfl_xor(q, 32);
;                         const float ri = rsqrtf(q * (1.f / 64.f) + EPS) * osc;
; #pragma unroll
;                         for (int bj = 0; bj < 2; ++bj)
; #pragma unroll
;                             for (int n = 0; n < 2; ++n) { const f32x4 g = *(const f32x4*)(gn + 32 * bj + 8 * fq + 4 * n); v[bj][n] = v[bj][n] * g * ri; }
;                     } else {
;                         const int pos = row & (SEQ - 1);
; #pragma unroll
;                         for (int n = 0; n < 2; ++n) { const f32x4 cs = *(const f32x4*)(rot + pos * 32 + 8 * fq + 4 * n), sn = *(const f32x4*)(rot + 4096 * 32 + pos * 32 + 8 * fq + 4 * n);
;                             const f32x4 x1 = v[0][n], x2 = v[1][n]; v[0][n] = (x1 * cs - x2 * sn) * osc; v[1][n] = (x2 * cs + x1 * sn) * osc; }
;                     }
; #pragma unroll
;                     for (int bj = 0; bj < 2; ++bj) { u32x4 w; w.x = cvt_pk_bf16(v[bj][0][0], v[bj][0][1]); w.y = cvt_pk_bf16(v[bj][0][2], v[bj][0][3]); w.z = cvt_pk_bf16(v[bj][1][0], v[bj][1][1]); w.w = cvt_pk_bf16(v[bj][1][2], v[bj][1][3]);
;                         *(u32x4*)(dst + (size_t)row * pitch + colt + cwh + 32 * bj) = w; }
.LBB0_361:
	v_ashrrev_i32_e32 v0, 31, v114
	v_mul_lo_u32 v100, s63, v114
	v_mul_lo_u32 v0, s62, v0
	v_mad_u64_u32 v[98:99], s[26:27], s62, v114, 0
	v_add3_u32 v99, v99, v0, v100
	v_lshl_add_u64 v[98:99], v[98:99], 1, v[168:169]
	v_cvt_pk_bf16_f32 v82, v82, v83
	v_cvt_pk_bf16_f32 v83, v84, v85
	v_cvt_pk_bf16_f32 v84, v86, v87
	v_cvt_pk_bf16_f32 v85, v88, v89
	global_store_dwordx4 v[98:99], v[82:85], off nt
	s_and_b64 vcc, exec, s[8:9]
	s_mov_b64 s[64:65], -1
	v_cvt_pk_bf16_f32 v82, v94, v95
	v_cvt_pk_bf16_f32 v83, v96, v97
	v_cvt_pk_bf16_f32 v84, v90, v91
	v_cvt_pk_bf16_f32 v85, v92, v93
	ds_read_b32 v0, v203 offset:192
	global_store_dwordx4 v[98:99], v[82:85], off offset:64 nt
	v_or_b32_e32 v98, 48, v202
	s_waitcnt lgkmcnt(0)
	v_pk_mul_f32 v[90:91], v[80:81], v[0:1] op_sel_hi:[1,0]
	v_pk_mul_f32 v[92:93], v[78:79], v[0:1] op_sel_hi:[1,0]
	v_pk_mul_f32 v[94:95], v[76:77], v[0:1] op_sel_hi:[1,0]
	v_pk_mul_f32 v[96:97], v[74:75], v[0:1] op_sel_hi:[1,0]
	v_pk_mul_f32 v[86:87], v[72:73], v[0:1] op_sel_hi:[1,0]
	v_pk_mul_f32 v[88:89], v[70:71], v[0:1] op_sel_hi:[1,0]
	v_pk_mul_f32 v[82:83], v[68:69], v[0:1] op_sel_hi:[1,0]
	v_pk_mul_f32 v[84:85], v[66:67], v[0:1] op_sel_hi:[1,0]
	s_cbranch_vccnz .LBB0_363
	v_lshlrev_b32_e32 v0, 7, v98
	v_and_b32_e32 v0, 0x7ff80, v0
	v_lshl_add_u64 v[66:67], v[142:143], 0, v[0:1]
	v_lshl_add_u64 v[68:69], v[144:145], 0, v[0:1]
	global_load_dwordx4 v[74:77], v[66:67], off offset:16
	global_load_dwordx4 v[70:73], v[66:67], off
	global_load_dwordx4 v[100:103], v[68:69], off offset:16
	global_load_dwordx4 v[78:81], v[68:69], off
	v_mov_b32_e32 v106, v164
	v_mov_b32_e32 v107, v164
	s_mov_b64 s[64:65], 0
	s_waitcnt vmcnt(0)
	v_pk_mul_f32 v[66:67], v[86:87], v[80:81]
	v_pk_mul_f32 v[68:69], v[88:89], v[78:79]
	v_pk_mul_f32 v[80:81], v[90:91], v[80:81]
	v_pk_mul_f32 v[78:79], v[92:93], v[78:79]
	v_pk_fma_f32 v[66:67], v[90:91], v[72:73], v[66:67] neg_lo:[0,0,1] neg_hi:[0,0,1]
	v_pk_fma_f32 v[104:105], v[92:93], v[70:71], v[68:69] neg_lo:[0,0,1] neg_hi:[0,0,1]
	v_pk_fma_f32 v[72:73], v[86:87], v[72:73], v[80:81]
	v_pk_fma_f32 v[70:71], v[88:89], v[70:71], v[78:79]
	v_pk_mul_f32 v[80:81], v[106:107], v[72:73]
	v_pk_mul_f32 v[78:79], v[164:165], v[70:71]
	v_pk_mul_f32 v[70:71], v[82:83], v[102:103]
	v_pk_mul_f32 v[72:73], v[84:85], v[100:101]
	v_pk_mul_f32 v[102:103], v[94:95], v[102:103]
	v_pk_mul_f32 v[100:101], v[96:97], v[100:101]
	v_pk_mul_f32 v[68:69], v[106:107], v[66:67]
	v_pk_mul_f32 v[66:67], v[164:165], v[104:105]
	v_pk_fma_f32 v[70:71], v[94:95], v[76:77], v[70:71] neg_lo:[0,0,1] neg_hi:[0,0,1]
	v_pk_fma_f32 v[104:105], v[96:97], v[74:75], v[72:73] neg_lo:[0,0,1] neg_hi:[0,0,1]
	v_pk_fma_f32 v[76:77], v[82:83], v[76:77], v[102:103]
	v_pk_fma_f32 v[74:75], v[84:85], v[74:75], v[100:101]
	v_pk_mul_f32 v[72:73], v[106:107], v[70:71]
	v_pk_mul_f32 v[70:71], v[164:165], v[104:105]
	v_pk_mul_f32 v[76:77], v[106:107], v[76:77]
	v_pk_mul_f32 v[74:75], v[164:165], v[74:75]

; __device__ __forceinline__ unsigned cvt_pk_bf16(float lo, float hi) { unsigned r; asm volatile("v_cvt_pk_bf16_f32 %0, %1, %2" : "=v"(r) : "v"(lo), "v"(hi)); return r; }
;     __device__ __forceinline__ void operator()(const f32x4 (&acc)[2][2][4][2], const pg8::Unit& u, int wr, int wc, int fr, int fq, LAS unsigned char* sp) const {
;     ...
;                     const int row = row0 + ai * 128 + m * 16; const float s = rsl[ai * 128 + m * 16];
;                     f32x4 v[2][2];
; #pragma unroll
;                     for (int bj = 0; bj < 2; ++bj)
; #pragma unroll
;                         for (int n = 0; n < 2; ++n) v[bj][n] = acc[ai][bj][m][n] * s;
;                     if (act == 3) {
;                         float q = 0.f;
; #pragma unroll
;                         for (int bj = 0; bj < 2; ++bj)
; #pragma unroll
;                             for (int n = 0; n < 2; ++n) q += (v[bj][n][0] * v[bj][n][0] + v[bj][n][1] * v[bj][n][1]) + (v[bj][n][2] * v[bj][n][2] + v[bj][n][3] * v[bj][n][3]);
;                         q += __shfl_xor(q, 16); q += __shfl_xor(q, 32);
;                         const float ri = rsqrtf(q * (1.f / 64.f) + EPS) * osc;
; #pragma unroll
;                         for (int bj = 0; bj < 2; ++bj)
; #pragma unroll
;                             for (int n = 0; n < 2; ++n) { const f32x4 g = *(const f32x4*)(gn + 32 * bj + 8 * fq + 4 * n); v[bj][n] = v[bj][n] * g * ri; }
;                     } else {
;                         const int pos = row & (SEQ - 1);
; #pragma unroll
;                         for (int n = 0; n < 2; ++n) { const f32x4 cs = *(const f32x4*)(rot + pos * 32 + 8 * fq + 4 * n), sn = *(const f32x4*)(rot + 4096 * 32 + pos * 32 + 8 * fq + 4 * n);
;                             const f32x4 x1 = v[0][n], x2 = v[1][n]; v[0][n] = (x1 * cs - x2 * sn) * osc; v[1][n] = (x2 * cs + x1 * sn) * osc; }
;                     }
; #pragma unroll
;                     for (int bj = 0; bj < 2; ++bj) { u32x4 w; w.x = cvt_pk_bf16(v[bj][0][0], v[bj][0][1]); w.y = cvt_pk_bf16(v[bj][0][2], v[bj][0][3]); w.z = cvt_pk_bf16(v[bj][1][0], v[bj][1][1]); w.w = cvt_pk_bf16(v[bj][1][2], v[bj][1][3]);
;                         *(u32x4*)(dst + (size_t)row * pitch + colt + cwh + 32 * bj) = w; }
.LBB0_365:
	v_ashrrev_i32_e32 v0, 31, v98
	v_mul_lo_u32 v84, s63, v98
	v_mul_lo_u32 v0, s62, v0
	v_mad_u64_u32 v[82:83], s[26:27], s62, v98, 0
	v_add3_u32 v83, v83, v0, v84
	v_lshl_add_u64 v[82:83], v[82:83], 1, v[168:169]
	v_cvt_pk_bf16_f32 v66, v66, v67
	v_cvt_pk_bf16_f32 v67, v68, v69
	v_cvt_pk_bf16_f32 v68, v70, v71
	v_cvt_pk_bf16_f32 v69, v72, v73
	global_store_dwordx4 v[82:83], v[66:69], off nt
	s_and_b64 vcc, exec, s[8:9]
	s_mov_b64 s[64:65], -1
	v_cvt_pk_bf16_f32 v66, v78, v79
	v_cvt_pk_bf16_f32 v67, v80, v81
	v_cvt_pk_bf16_f32 v68, v74, v75
	v_cvt_pk_bf16_f32 v69, v76, v77
	ds_read_b32 v0, v203 offset:512
	global_store_dwordx4 v[82:83], v[66:69], off offset:64 nt
	v_add_u32_e32 v82, 0x80, v202
	s_waitcnt lgkmcnt(0)
	v_pk_mul_f32 v[74:75], v[64:65], v[0:1] op_sel_hi:[1,0]
	v_pk_mul_f32 v[76:77], v[62:63], v[0:1] op_sel_hi:[1,0]
	v_pk_mul_f32 v[78:79], v[60:61], v[0:1] op_sel_hi:[1,0]
	v_pk_mul_f32 v[80:81], v[58:59], v[0:1] op_sel_hi:[1,0]
	v_pk_mul_f32 v[70:71], v[56:57], v[0:1] op_sel_hi:[1,0]
	v_pk_mul_f32 v[72:73], v[54:55], v[0:1] op_sel_hi:[1,0]
	v_pk_mul_f32 v[66:67], v[52:53], v[0:1] op_sel_hi:[1,0]
	v_pk_mul_f32 v[68:69], v[50:51], v[0:1] op_sel_hi:[1,0]
	s_cbranch_vccnz .LBB0_367
	v_lshlrev_b32_e32 v0, 7, v82
	v_and_b32_e32 v0, 0x7e780, v0
	v_lshl_add_u64 v[50:51], v[142:143], 0, v[0:1]
	v_lshl_add_u64 v[52:53], v[144:145], 0, v[0:1]
	global_load_dwordx4 v[58:61], v[50:51], off offset:16
	global_load_dwordx4 v[54:57], v[50:51], off
	global_load_dwordx4 v[84:87], v[52:53], off offset:16
	global_load_dwordx4 v[62:65], v[52:53], off
	v_mov_b32_e32 v90, v164
	v_mov_b32_e32 v91, v164
	s_mov_b64 s[64:65], 0
	s_waitcnt vmcnt(0)
	v_pk_mul_f32 v[50:51], v[70:71], v[64:65]
	v_pk_mul_f32 v[52:53], v[72:73], v[62:63]
	v_pk_mul_f32 v[64:65], v[74:75], v[64:65]
	v_pk_mul_f32 v[62:63], v[76:77], v[62:63]
	v_pk_fma_f32 v[50:51], v[74:75], v[56:57], v[50:51] neg_lo:[0,0,1] neg_hi:[0,0,1]
	v_pk_fma_f32 v[88:89], v[76:77], v[54:55], v[52:53] neg_lo:[0,0,1] neg_hi:[0,0,1]
	v_pk_fma_f32 v[56:57], v[70:71], v[56:57], v[64:65]
	v_pk_fma_f32 v[54:55], v[72:73], v[54:55], v[62:63]
	v_pk_mul_f32 v[64:65], v[90:91], v[56:57]
	v_pk_mul_f32 v[62:63], v[164:165], v[54:55]
	v_pk_mul_f32 v[54:55], v[66:67], v[86:87]
	v_pk_mul_f32 v[56:57], v[68:69], v[84:85]
	v_pk_mul_f32 v[86:87], v[78:79], v[86:87]
	v_pk_mul_f32 v[84:85], v[80:81], v[84:85]
	v_pk_mul_f32 v[52:53], v[90:91], v[50:51]
	v_pk_mul_f32 v[50:51], v[164:165], v[88:89]
	v_pk_fma_f32 v[54:55], v[78:79], v[60:61], v[54:55] neg_lo:[0,0,1] neg_hi:[0,0,1]
	v_pk_fma_f32 v[88:89], v[80:81], v[58:59], v[56:57] neg_lo:[0,0,1] neg_hi:[0,0,1]
	v_pk_fma_f32 v[60:61], v[66:67], v[60:61], v[86:87]
	v_pk_fma_f32 v[58:59], v[68:69], v[58:59], v[84:85]
	v_pk_mul_f32 v[56:57], v[90:91], v[54:55]
	v_pk_mul_f32 v[54:55], v[164:165], v[88:89]
	v_pk_mul_f32 v[60:61], v[90:91], v[60:61]
	v_pk_mul_f32 v[58:59], v[164:165], v[58:59]

; __device__ __forceinline__ unsigned cvt_pk_bf16(float lo, float hi) { unsigned r; asm volatile("v_cvt_pk_bf16_f32 %0, %1, %2" : "=v"(r) : "v"(lo), "v"(hi)); return r; }
;     __device__ __forceinline__ void operator()(const f32x4 (&acc)[2][2][4][2], const pg8::Unit& u, int wr, int wc, int fr, int fq, LAS unsigned char* sp) const {
;     ...
;                     const int row = row0 + ai * 128 + m * 16; const float s = rsl[ai * 128 + m * 16];
;                     f32x4 v[2][2];
; #pragma unroll
;                     for (int bj = 0; bj < 2; ++bj)
; #pragma unroll
;                         for (int n = 0; n < 2; ++n) v[bj][n] = acc[ai][bj][m][n] * s;
;                     if (act == 3) {
;                         float q = 0.f;
; #pragma unroll
;                         for (int bj = 0; bj < 2; ++bj)
; #pragma unroll
;                             for (int n = 0; n < 2; ++n) q += (v[bj][n][0] * v[bj][n][0] + v[bj][n][1] * v[bj][n][1]) + (v[bj][n][2] * v[bj][n][2] + v[bj][n][3] * v[bj][n][3]);
;                         q += __shfl_xor(q, 16); q += __shfl_xor(q, 32);
;                         const float ri = rsqrtf(q * (1.f / 64.f) + EPS) * osc;
; #pragma unroll
;                         for (int bj = 0; bj < 2; ++bj)
; #pragma unroll
;                             for (int n = 0; n < 2; ++n) { const f32x4 g = *(const f32x4*)(gn + 32 * bj + 8 * fq + 4 * n); v[bj][n] = v[bj][n] * g * ri; }
;                     } else {
;                         const int pos = row & (SEQ - 1);
; #pragma unroll
;                         for (int n = 0; n < 2; ++n) { const f32x4 cs = *(const f32x4*)(rot + pos * 32 + 8 * fq + 4 * n), sn = *(const f32x4*)(rot + 4096 * 32 + pos * 32 + 8 * fq + 4 * n);
;                             const f32x4 x1 = v[0][n], x2 = v[1][n]; v[0][n] = (x1 * cs - x2 * sn) * osc; v[1][n] = (x2 * cs + x1 * sn) * osc; }
;                     }
; #pragma unroll
;                     for (int bj = 0; bj < 2; ++bj) { u32x4 w; w.x = cvt_pk_bf16(v[bj][0][0], v[bj][0][1]); w.y = cvt_pk_bf16(v[bj][0][2], v[bj][0][3]); w.z = cvt_pk_bf16(v[bj][1][0], v[bj][1][1]); w.w = cvt_pk_bf16(v[bj][1][2], v[bj][1][3]);
;                         *(u32x4*)(dst + (size_t)row * pitch + colt + cwh + 32 * bj) = w; }
.LBB0_369:
	v_ashrrev_i32_e32 v0, 31, v82
	v_mul_lo_u32 v68, s63, v82
	v_mul_lo_u32 v0, s62, v0
	v_mad_u64_u32 v[66:67], s[26:27], s62, v82, 0
	v_add3_u32 v67, v67, v0, v68
	v_lshl_add_u64 v[66:67], v[66:67], 1, v[168:169]
	v_cvt_pk_bf16_f32 v50, v50, v51
	v_cvt_pk_bf16_f32 v51, v52, v53
	v_cvt_pk_bf16_f32 v52, v54, v55
	v_cvt_pk_bf16_f32 v53, v56, v57
	global_store_dwordx4 v[66:67], v[50:53], off nt
	s_and_b64 vcc, exec, s[8:9]
	s_mov_b64 s[64:65], -1
	v_cvt_pk_bf16_f32 v50, v62, v63
	v_cvt_pk_bf16_f32 v51, v64, v65
	v_cvt_pk_bf16_f32 v52, v58, v59
	v_cvt_pk_bf16_f32 v53, v60, v61
	ds_read_b32 v0, v203 offset:576
	global_store_dwordx4 v[66:67], v[50:53], off offset:64 nt
	v_add_u32_e32 v66, 0x90, v202
	s_waitcnt lgkmcnt(0)
	v_pk_mul_f32 v[58:59], v[48:49], v[0:1] op_sel_hi:[1,0]
	v_pk_mul_f32 v[60:61], v[46:47], v[0:1] op_sel_hi:[1,0]
	v_pk_mul_f32 v[62:63], v[44:45], v[0:1] op_sel_hi:[1,0]
	v_pk_mul_f32 v[64:65], v[42:43], v[0:1] op_sel_hi:[1,0]
	v_pk_mul_f32 v[54:55], v[40:41], v[0:1] op_sel_hi:[1,0]
	v_pk_mul_f32 v[56:57], v[38:39], v[0:1] op_sel_hi:[1,0]
	v_pk_mul_f32 v[50:51], v[36:37], v[0:1] op_sel_hi:[1,0]
	v_pk_mul_f32 v[52:53], v[34:35], v[0:1] op_sel_hi:[1,0]
	s_cbranch_vccnz .LBB0_371
	v_lshlrev_b32_e32 v0, 7, v66
	v_and_b32_e32 v0, 0x7ef80, v0
	v_lshl_add_u64 v[34:35], v[142:143], 0, v[0:1]
	v_lshl_add_u64 v[36:37], v[144:145], 0, v[0:1]
	global_load_dwordx4 v[42:45], v[34:35], off offset:16
	global_load_dwordx4 v[38:41], v[34:35], off
	global_load_dwordx4 v[68:71], v[36:37], off offset:16
	global_load_dwordx4 v[46:49], v[36:37], off
	v_mov_b32_e32 v74, v164
	v_mov_b32_e32 v75, v164
	s_mov_b64 s[64:65], 0
	s_waitcnt vmcnt(0)
	v_pk_mul_f32 v[34:35], v[54:55], v[48:49]
	v_pk_mul_f32 v[36:37], v[56:57], v[46:47]
	v_pk_mul_f32 v[48:49], v[58:59], v[48:49]
	v_pk_mul_f32 v[46:47], v[60:61], v[46:47]
	v_pk_fma_f32 v[34:35], v[58:59], v[40:41], v[34:35] neg_lo:[0,0,1] neg_hi:[0,0,1]
	v_pk_fma_f32 v[72:73], v[60:61], v[38:39], v[36:37] neg_lo:[0,0,1] neg_hi:[0,0,1]
	v_pk_fma_f32 v[40:41], v[54:55], v[40:41], v[48:49]
	v_pk_fma_f32 v[38:39], v[56:57], v[38:39], v[46:47]
	v_pk_mul_f32 v[48:49], v[74:75], v[40:41]
	v_pk_mul_f32 v[46:47], v[164:165], v[38:39]
	v_pk_mul_f32 v[38:39], v[50:51], v[70:71]
	v_pk_mul_f32 v[40:41], v[52:53], v[68:69]
	v_pk_mul_f32 v[70:71], v[62:63], v[70:71]
	v_pk_mul_f32 v[68:69], v[64:65], v[68:69]
	v_pk_mul_f32 v[36:37], v[74:75], v[34:35]
	v_pk_mul_f32 v[34:35], v[164:165], v[72:73]
	v_pk_fma_f32 v[38:39], v[62:63], v[44:45], v[38:39] neg_lo:[0,0,1] neg_hi:[0,0,1]
	v_pk_fma_f32 v[72:73], v[64:65], v[42:43], v[40:41] neg_lo:[0,0,1] neg_hi:[0,0,1]
	v_pk_fma_f32 v[44:45], v[50:51], v[44:45], v[70:71]
	v_pk_fma_f32 v[42:43], v[52:53], v[42:43], v[68:69]
	v_pk_mul_f32 v[40:41], v[74:75], v[38:39]
	v_pk_mul_f32 v[38:39], v[164:165], v[72:73]
	v_pk_mul_f32 v[44:45], v[74:75], v[44:45]
	v_pk_mul_f32 v[42:43], v[164:165], v[42:43]

; __device__ __forceinline__ unsigned cvt_pk_bf16(float lo, float hi) { unsigned r; asm volatile("v_cvt_pk_bf16_f32 %0, %1, %2" : "=v"(r) : "v"(lo), "v"(hi)); return r; }
;     __device__ __forceinline__ void operator()(const f32x4 (&acc)[2][2][4][2], const pg8::Unit& u, int wr, int wc, int fr, int fq, LAS unsigned char* sp) const {
;     ...
;                     const int row = row0 + ai * 128 + m * 16; const float s = rsl[ai * 128 + m * 16];
;                     f32x4 v[2][2];
; #pragma unroll
;                     for (int bj = 0; bj < 2; ++bj)
; #pragma unroll
;                         for (int n = 0; n < 2; ++n) v[bj][n] = acc[ai][bj][m][n] * s;
;                     if (act == 3) {
;                         float q = 0.f;
; #pragma unroll
;                         for (int bj = 0; bj < 2; ++bj)
; #pragma unroll
;                             for (int n = 0; n < 2; ++n) q += (v[bj][n][0] * v[bj][n][0] + v[bj][n][1] * v[bj][n][1]) + (v[bj][n][2] * v[bj][n][2] + v[bj][n][3] * v[bj][n][3]);
;                         q += __shfl_xor(q, 16); q += __shfl_xor(q, 32);
;                         const float ri = rsqrtf(q * (1.f / 64.f) + EPS) * osc;
; #pragma unroll
;                         for (int bj = 0; bj < 2; ++bj)
; #pragma unroll
;                             for (int n = 0; n < 2; ++n) { const f32x4 g = *(const f32x4*)(gn + 32 * bj + 8 * fq + 4 * n); v[bj][n] = v[bj][n] * g * ri; }
;                     } else {
;                         const int pos = row & (SEQ - 1);
; #pragma unroll
;                         for (int n = 0; n < 2; ++n) { const f32x4 cs = *(const f32x4*)(rot + pos * 32 + 8 * fq + 4 * n), sn = *(const f32x4*)(rot + 4096 * 32 + pos * 32 + 8 * fq + 4 * n);
;                             const f32x4 x1 = v[0][n], x2 = v[1][n]; v[0][n] = (x1 * cs - x2 * sn) * osc; v[1][n] = (x2 * cs + x1 * sn) * osc; }
;                     }
; #pragma unroll
;                     for (int bj = 0; bj < 2; ++bj) { u32x4 w; w.x = cvt_pk_bf16(v[bj][0][0], v[bj][0][1]); w.y = cvt_pk_bf16(v[bj][0][2], v[bj][0][3]); w.z = cvt_pk_bf16(v[bj][1][0], v[bj][1][1]); w.w = cvt_pk_bf16(v[bj][1][2], v[bj][1][3]);
;                         *(u32x4*)(dst + (size_t)row * pitch + colt + cwh + 32 * bj) = w; }
.LBB0_373:
	v_ashrrev_i32_e32 v0, 31, v66
	v_mul_lo_u32 v52, s63, v66
	v_mul_lo_u32 v0, s62, v0
	v_mad_u64_u32 v[50:51], s[26:27], s62, v66, 0
	v_add3_u32 v51, v51, v0, v52
	v_lshl_add_u64 v[50:51], v[50:51], 1, v[168:169]
	v_cvt_pk_bf16_f32 v34, v34, v35
	v_cvt_pk_bf16_f32 v35, v36, v37
	v_cvt_pk_bf16_f32 v36, v38, v39
	v_cvt_pk_bf16_f32 v37, v40, v41
	global_store_dwordx4 v[50:51], v[34:37], off nt
	s_and_b64 vcc, exec, s[8:9]
	s_mov_b64 s[64:65], -1
	v_cvt_pk_bf16_f32 v34, v46, v47
	v_cvt_pk_bf16_f32 v35, v48, v49
	v_cvt_pk_bf16_f32 v36, v42, v43
	v_cvt_pk_bf16_f32 v37, v44, v45
	ds_read_b32 v0, v203 offset:640
	global_store_dwordx4 v[50:51], v[34:37], off offset:64 nt
	v_add_u32_e32 v50, 0xa0, v202
	s_waitcnt lgkmcnt(0)
	v_pk_mul_f32 v[42:43], v[32:33], v[0:1] op_sel_hi:[1,0]
	v_pk_mul_f32 v[44:45], v[30:31], v[0:1] op_sel_hi:[1,0]
	v_pk_mul_f32 v[46:47], v[28:29], v[0:1] op_sel_hi:[1,0]
	v_pk_mul_f32 v[48:49], v[26:27], v[0:1] op_sel_hi:[1,0]
	v_pk_mul_f32 v[38:39], v[24:25], v[0:1] op_sel_hi:[1,0]
	v_pk_mul_f32 v[40:41], v[22:23], v[0:1] op_sel_hi:[1,0]
	v_pk_mul_f32 v[34:35], v[20:21], v[0:1] op_sel_hi:[1,0]
	v_pk_mul_f32 v[36:37], v[18:19], v[0:1] op_sel_hi:[1,0]
	s_cbranch_vccnz .LBB0_375
	v_lshlrev_b32_e32 v0, 7, v50
	v_and_b32_e32 v0, 0x7f780, v0
	v_lshl_add_u64 v[18:19], v[142:143], 0, v[0:1]
	v_lshl_add_u64 v[20:21], v[144:145], 0, v[0:1]
	global_load_dwordx4 v[26:29], v[18:19], off offset:16
	global_load_dwordx4 v[22:25], v[18:19], off
	global_load_dwordx4 v[52:55], v[20:21], off offset:16
	global_load_dwordx4 v[30:33], v[20:21], off
	v_mov_b32_e32 v58, v164
	v_mov_b32_e32 v59, v164
	s_mov_b64 s[64:65], 0
	s_waitcnt vmcnt(0)
	v_pk_mul_f32 v[18:19], v[38:39], v[32:33]
	v_pk_mul_f32 v[20:21], v[40:41], v[30:31]
	v_pk_mul_f32 v[32:33], v[42:43], v[32:33]
	v_pk_mul_f32 v[30:31], v[44:45], v[30:31]
	v_pk_fma_f32 v[18:19], v[42:43], v[24:25], v[18:19] neg_lo:[0,0,1] neg_hi:[0,0,1]
	v_pk_fma_f32 v[56:57], v[44:45], v[22:23], v[20:21] neg_lo:[0,0,1] neg_hi:[0,0,1]
	v_pk_fma_f32 v[24:25], v[38:39], v[24:25], v[32:33]
	v_pk_fma_f32 v[22:23], v[40:41], v[22:23], v[30:31]
	v_pk_mul_f32 v[32:33], v[58:59], v[24:25]
	v_pk_mul_f32 v[30:31], v[164:165], v[22:23]
	v_pk_mul_f32 v[22:23], v[34:35], v[54:55]
	v_pk_mul_f32 v[24:25], v[36:37], v[52:53]
	v_pk_mul_f32 v[54:55], v[46:47], v[54:55]
	v_pk_mul_f32 v[52:53], v[48:49], v[52:53]
	v_pk_mul_f32 v[20:21], v[58:59], v[18:19]
	v_pk_mul_f32 v[18:19], v[164:165], v[56:57]
	v_pk_fma_f32 v[22:23], v[46:47], v[28:29], v[22:23] neg_lo:[0,0,1] neg_hi:[0,0,1]
	v_pk_fma_f32 v[56:57], v[48:49], v[26:27], v[24:25] neg_lo:[0,0,1] neg_hi:[0,0,1]
	v_pk_fma_f32 v[28:29], v[34:35], v[28:29], v[54:55]
	v_pk_fma_f32 v[26:27], v[36:37], v[26:27], v[52:53]
	v_pk_mul_f32 v[24:25], v[58:59], v[22:23]
	v_pk_mul_f32 v[22:23], v[164:165], v[56:57]
	v_pk_mul_f32 v[28:29], v[58:59], v[28:29]
	v_pk_mul_f32 v[26:27], v[164:165], v[26:27]

; __device__ __forceinline__ unsigned cvt_pk_bf16(float lo, float hi) { unsigned r; asm volatile("v_cvt_pk_bf16_f32 %0, %1, %2" : "=v"(r) : "v"(lo), "v"(hi)); return r; }
;     __device__ __forceinline__ void operator()(const f32x4 (&acc)[2][2][4][2], const pg8::Unit& u, int wr, int wc, int fr, int fq, LAS unsigned char* sp) const {
;     ...
;                     const int row = row0 + ai * 128 + m * 16; const float s = rsl[ai * 128 + m * 16];
;                     f32x4 v[2][2];
; #pragma unroll
;                     for (int bj = 0; bj < 2; ++bj)
; #pragma unroll
;                         for (int n = 0; n < 2; ++n) v[bj][n] = acc[ai][bj][m][n] * s;
;                     if (act == 3) {
;                         float q = 0.f;
; #pragma unroll
;                         for (int bj = 0; bj < 2; ++bj)
; #pragma unroll
;                             for (int n = 0; n < 2; ++n) q += (v[bj][n][0] * v[bj][n][0] + v[bj][n][1] * v[bj][n][1]) + (v[bj][n][2] * v[bj][n][2] + v[bj][n][3] * v[bj][n][3]);
;                         q += __shfl_xor(q, 16); q += __shfl_xor(q, 32);
;                         const float ri = rsqrtf(q * (1.f / 64.f) + EPS) * osc;
; #pragma unroll
;                         for (int bj = 0; bj < 2; ++bj)
; #pragma unroll
;                             for (int n = 0; n < 2; ++n) { const f32x4 g = *(const f32x4*)(gn + 32 * bj + 8 * fq + 4 * n); v[bj][n] = v[bj][n] * g * ri; }
;                     } else {
;                         const int pos = row & (SEQ - 1);
; #pragma unroll
;                         for (int n = 0; n < 2; ++n) { const f32x4 cs = *(const f32x4*)(rot + pos * 32 + 8 * fq + 4 * n), sn = *(const f32x4*)(rot + 4096 * 32 + pos * 32 + 8 * fq + 4 * n);
;                             const f32x4 x1 = v[0][n], x2 = v[1][n]; v[0][n] = (x1 * cs - x2 * sn) * osc; v[1][n] = (x2 * cs + x1 * sn) * osc; }
;                     }
; #pragma unroll
;                     for (int bj = 0; bj < 2; ++bj) { u32x4 w; w.x = cvt_pk_bf16(v[bj][0][0], v[bj][0][1]); w.y = cvt_pk_bf16(v[bj][0][2], v[bj][0][3]); w.z = cvt_pk_bf16(v[bj][1][0], v[bj][1][1]); w.w = cvt_pk_bf16(v[bj][1][2], v[bj][1][3]);
;                         *(u32x4*)(dst + (size_t)row * pitch + colt + cwh + 32 * bj) = w; }
.LBB0_377:
	v_ashrrev_i32_e32 v0, 31, v50
	v_mul_lo_u32 v36, s63, v50
	v_mul_lo_u32 v0, s62, v0
	v_mad_u64_u32 v[34:35], s[26:27], s62, v50, 0
	v_add3_u32 v35, v35, v0, v36
	v_lshl_add_u64 v[34:35], v[34:35], 1, v[168:169]
	v_cvt_pk_bf16_f32 v18, v18, v19
	v_cvt_pk_bf16_f32 v19, v20, v21
	v_cvt_pk_bf16_f32 v20, v22, v23
	v_cvt_pk_bf16_f32 v21, v24, v25
	global_store_dwordx4 v[34:35], v[18:21], off nt
	s_and_b64 vcc, exec, s[8:9]
	s_mov_b64 s[8:9], -1
	v_cvt_pk_bf16_f32 v18, v30, v31
	v_cvt_pk_bf16_f32 v19, v32, v33
	v_cvt_pk_bf16_f32 v20, v26, v27
	v_cvt_pk_bf16_f32 v21, v28, v29
	ds_read_b32 v0, v203 offset:704
	global_store_dwordx4 v[34:35], v[18:21], off offset:64 nt
	v_add_u32_e32 v34, 0xb0, v202
	s_waitcnt lgkmcnt(0)
	v_pk_mul_f32 v[26:27], v[16:17], v[0:1] op_sel_hi:[1,0]
	v_pk_mul_f32 v[28:29], v[14:15], v[0:1] op_sel_hi:[1,0]
	v_pk_mul_f32 v[30:31], v[12:13], v[0:1] op_sel_hi:[1,0]
	v_pk_mul_f32 v[32:33], v[10:11], v[0:1] op_sel_hi:[1,0]
	v_pk_mul_f32 v[22:23], v[8:9], v[0:1] op_sel_hi:[1,0]
	v_pk_mul_f32 v[24:25], v[6:7], v[0:1] op_sel_hi:[1,0]
	v_pk_mul_f32 v[18:19], v[4:5], v[0:1] op_sel_hi:[1,0]
	v_pk_mul_f32 v[20:21], v[2:3], v[0:1] op_sel_hi:[1,0]
	s_cbranch_vccnz .LBB0_379
	v_lshlrev_b32_e32 v0, 7, v34
	v_and_b32_e32 v0, 0x7ff80, v0
	v_lshl_add_u64 v[2:3], v[142:143], 0, v[0:1]
	v_lshl_add_u64 v[4:5], v[144:145], 0, v[0:1]
	global_load_dwordx4 v[10:13], v[2:3], off offset:16
	global_load_dwordx4 v[6:9], v[2:3], off
	global_load_dwordx4 v[36:39], v[4:5], off offset:16
	global_load_dwordx4 v[14:17], v[4:5], off
	v_mov_b32_e32 v42, v164
	v_mov_b32_e32 v43, v164
	s_mov_b64 s[8:9], 0
	s_waitcnt vmcnt(0)
	v_pk_mul_f32 v[2:3], v[22:23], v[16:17]
	v_pk_mul_f32 v[4:5], v[24:25], v[14:15]
	v_pk_mul_f32 v[16:17], v[26:27], v[16:17]
	v_pk_mul_f32 v[14:15], v[28:29], v[14:15]
	v_pk_fma_f32 v[2:3], v[26:27], v[8:9], v[2:3] neg_lo:[0,0,1] neg_hi:[0,0,1]
	v_pk_fma_f32 v[40:41], v[28:29], v[6:7], v[4:5] neg_lo:[0,0,1] neg_hi:[0,0,1]
	v_pk_fma_f32 v[8:9], v[22:23], v[8:9], v[16:17]
	v_pk_fma_f32 v[6:7], v[24:25], v[6:7], v[14:15]
	v_pk_mul_f32 v[16:17], v[42:43], v[8:9]
	v_pk_mul_f32 v[14:15], v[164:165], v[6:7]
	v_pk_mul_f32 v[6:7], v[18:19], v[38:39]
	v_pk_mul_f32 v[8:9], v[20:21], v[36:37]
	v_pk_mul_f32 v[38:39], v[30:31], v[38:39]
	v_pk_mul_f32 v[36:37], v[32:33], v[36:37]
	v_pk_mul_f32 v[4:5], v[42:43], v[2:3]
	v_pk_mul_f32 v[2:3], v[164:165], v[40:41]
	v_pk_fma_f32 v[6:7], v[30:31], v[12:13], v[6:7] neg_lo:[0,0,1] neg_hi:[0,0,1]
	v_pk_fma_f32 v[40:41], v[32:33], v[10:11], v[8:9] neg_lo:[0,0,1] neg_hi:[0,0,1]
	v_pk_fma_f32 v[12:13], v[18:19], v[12:13], v[38:39]
	v_pk_fma_f32 v[10:11], v[20:21], v[10:11], v[36:37]
	v_pk_mul_f32 v[8:9], v[42:43], v[6:7]
	v_pk_mul_f32 v[6:7], v[164:165], v[40:41]
	v_pk_mul_f32 v[12:13], v[42:43], v[12:13]
	v_pk_mul_f32 v[10:11], v[164:165], v[10:11]

; __device__ __forceinline__ unsigned cvt_pk_bf16(float lo, float hi) { unsigned r; asm volatile("v_cvt_pk_bf16_f32 %0, %1, %2" : "=v"(r) : "v"(lo), "v"(hi)); return r; }
;     __device__ __forceinline__ void operator()(const f32x4 (&acc)[2][2][4][2], const pg8::Unit& u, int wr, int wc, int fr, int fq, LAS unsigned char* sp) const {
;     ...
;                     for (int bj = 0; bj < 2; ++bj) { u32x4 w; w.x = cvt_pk_bf16(v[bj][0][0], v[bj][0][1]); w.y = cvt_pk_bf16(v[bj][0][2], v[bj][0][3]); w.z = cvt_pk_bf16(v[bj][1][0], v[bj][1][1]); w.w = cvt_pk_bf16(v[bj][1][2], v[bj][1][3]);
;                         *(u32x4*)(dst + (size_t)row * pitch + colt + cwh + 32 * bj) = w; }
.LBB0_381:
	v_ashrrev_i32_e32 v0, 31, v34
	v_mul_lo_u32 v20, s63, v34
	v_mul_lo_u32 v0, s62, v0
	v_mad_u64_u32 v[18:19], s[8:9], s62, v34, 0
	v_add3_u32 v19, v19, v0, v20
	v_lshl_add_u64 v[18:19], v[18:19], 1, v[168:169]
	v_cvt_pk_bf16_f32 v2, v2, v3
	v_cvt_pk_bf16_f32 v3, v4, v5
	v_cvt_pk_bf16_f32 v4, v6, v7
	v_cvt_pk_bf16_f32 v5, v8, v9
	global_store_dwordx4 v[18:19], v[2:5], off nt
	s_nop 1
	v_cvt_pk_bf16_f32 v2, v14, v15
	v_cvt_pk_bf16_f32 v3, v16, v17
	v_cvt_pk_bf16_f32 v4, v10, v11
	v_cvt_pk_bf16_f32 v5, v12, v13
	global_store_dwordx4 v[18:19], v[2:5], off offset:64 nt
	s_andn2_b64 vcc, exec, s[6:7]
	s_mov_b64 s[6:7], -1
	s_cbranch_vccnz .LBB0_235
